# GU GEMM: next tile's first A/B loads (addresses by tile delta) issued before the epilogue and kept in flight across it; B LDS ring relocated above the epilogue staging area
# speedup vs baseline: 1.0016x; 1.0016x over previous
.LBB0_215:
	s_mul_hi_i32 s0, s8, 0x2aaaaaab
	s_lshr_b32 s1, s0, 31
	s_ashr_i32 s0, s0, 5
	s_add_i32 s0, s0, s1
	s_lshl_b32 s1, s0, 3
	s_sub_i32 s2, 17, s1
	s_min_u32 s2, s2, 8
	v_cvt_f32_ubyte0_e32 v0, s2
	v_rcp_iflag_f32_e32 v0, v0
	s_sub_i32 s5, 0, s2
	s_mulk_i32 s0, 0xff40
	s_add_i32 s3, s0, s8
	v_mul_f32_e32 v0, 0x4f7ffffe, v0
	v_cvt_u32_f32_e32 v0, v0
	s_abs_i32 s4, s3
	s_ashr_i32 s0, s3, 31
	v_mov_b32_e32 v181, v179
	v_readfirstlane_b32 s6, v0
	s_mul_i32 s5, s5, s6
	s_mul_hi_u32 s5, s6, s5
	s_add_i32 s6, s6, s5
	s_mul_hi_u32 s5, s4, s6
	s_mul_i32 s6, s5, s2
	s_sub_i32 s4, s4, s6
	s_add_i32 s6, s5, 1
	s_sub_i32 s7, s4, s2
	s_cmp_ge_u32 s4, s2
	s_cselect_b32 s5, s6, s5
	s_cselect_b32 s4, s7, s4
	s_add_i32 s6, s5, 1
	s_cmp_ge_u32 s4, s2
	s_cselect_b32 s4, s6, s5
	s_xor_b32 s4, s4, s0
	s_sub_i32 s0, s4, s0
	s_mul_i32 s2, s2, s0
	s_sub_i32 s2, s3, s2
	s_add_i32 s1, s1, s11
	s_add_i32 s2, s1, s2
	v_ashrrev_i32_e32 v233, 6, v181
	v_lshlrev_b32_e32 v0, 1, v233
	v_lshl_add_u32 v0, s2, 3, v0
	v_ashrrev_i32_e32 v1, 31, v0
	v_bfe_u32 v183, v181, 5, 1
	v_lshlrev_b64 v[0:1], 16, v[0:1]
	v_and_b32_e32 v231, 31, v181
	v_lshl_add_u64 v[0:1], s[64:65], 0, v[0:1]
	v_lshlrev_b32_e32 v176, 9, v183
	s_ashr_i32 s1, s0, 31
	v_lshl_add_u64 v[0:1], v[0:1], 0, v[176:177]
	v_lshlrev_b32_e32 v176, 4, v231
	v_ashrrev_i32_e32 v12, 2, v181
	s_lshl_b64 s[4:5], s[0:1], 18
	v_lshl_add_u64 v[184:185], v[0:1], 0, v[176:177]
	s_add_u32 s4, s9, s4
	v_lshlrev_b32_e32 v0, 5, v12
	s_addc_u32 s5, s10, s5
	v_ashrrev_i32_e32 v1, 31, v0
	v_lshlrev_b32_e32 v2, 4, v181
	v_lshl_add_u64 v[0:1], v[0:1], 1, s[4:5]
	v_and_b32_e32 v176, 48, v2
	v_lshl_add_u64 v[186:187], v[0:1], 0, v[176:177]
	s_movk_i32 s1, 0x2000
	v_add_co_u32_e32 v8, vcc, s1, v186
	v_mul_u32_u24_e32 v10, 40, v231
	s_nop 0
	v_addc_co_u32_e32 v9, vcc, 0, v187, vcc
	v_lshlrev_b32_e32 v11, 4, v183
	v_lshl_add_u32 v235, v10, 1, v11
	v_add_co_u32_e32 v10, vcc, s41, v184
	s_movk_i32 s3, 0x50
	s_nop 0
	v_addc_co_u32_e32 v11, vcc, 0, v185, vcc
	v_and_b32_e32 v232, 63, v181
	v_lshlrev_b32_e32 v234, 3, v181
	v_lshrrev_b32_e32 v176, 6, v181
	v_lshlrev_b32_e32 v197, 11, v176
	s_nop 0
	v_readfirstlane_b32 vcc_lo, v197
	v_bfe_u32 v197, v181, 4, 2
	v_lshlrev_b32_e32 v197, 1, v197
	v_mov_b32_e32 v176, 0x78
	v_lshrrev_b32_e32 v197, v197, v176
	v_and_b32_e32 v197, 3, v197
	v_and_b32_e32 v196, 3, v181
	v_xor_b32_e32 v197, v197, v196
	v_lshlrev_b32_e32 v197, 4, v197
	v_and_b32_e32 v188, 0xffffffcf, v186
	v_or_b32_e32 v188, v188, v197
	v_mov_b32_e32 v189, v187
	v_lshrrev_b32_e32 v176, 6, v181
	v_lshlrev_b32_e32 v176, 10, v176
	v_lshl_add_u64 v[188:189], v[188:189], 0, v[176:177]
	v_bfe_u32 v197, v181, 4, 1
	v_lshlrev_b32_e32 v176, 9, v183
	v_lshl_add_u32 v176, v197, 8, v176
	v_lshl_add_u64 v[184:185], v[184:185], 0, v[176:177]
	v_mov_b32_e32 v176, s41
	v_lshl_add_u64 v[186:187], v[184:185], 0, v[176:177]
	v_mov_b32_e32 v176, 0x78
	v_bfe_u32 v197, v181, 2, 2
	v_lshlrev_b32_e32 v197, 1, v197
	v_lshrrev_b32_e32 v197, v197, v176
	v_and_b32_e32 v197, 3, v197
	v_bfe_u32 v196, v181, 4, 2
	v_xor_b32_e32 v197, v197, v196
	v_lshlrev_b32_e32 v197, 4, v197
	v_and_b32_e32 v196, 15, v181
	v_lshl_add_u32 v196, v196, 6, v197
	s_mov_b32 s96, 0
	s_mov_b32 m0, vcc_lo
	v_lshl_add_u64 v[160:161], v[188:189], 0, s[96:97]
	global_load_lds_dwordx4 v[160:161], off
	global_load_lds_dwordx4 v[160:161], off offset:1024
	s_mov_b32 s96, 0
	v_lshl_add_u64 v[198:199], v[184:185], 0, s[96:97]
	v_lshl_add_u64 v[200:201], v[186:187], 0, s[96:97]
	global_load_dwordx4 v[128:131], v[198:199], off
	global_load_dwordx4 v[132:135], v[198:199], off offset:256
	global_load_dwordx4 v[136:139], v[200:201], off
	global_load_dwordx4 v[140:143], v[200:201], off offset:256
	s_movk_i32 s96, 0x2000
	s_add_i32 m0, vcc_lo, 8192
	v_lshl_add_u64 v[160:161], v[188:189], 0, s[96:97]
	global_load_lds_dwordx4 v[160:161], off
	global_load_lds_dwordx4 v[160:161], off offset:1024
	s_movk_i32 s96, 0x800
	v_lshl_add_u64 v[198:199], v[184:185], 0, s[96:97]
	v_lshl_add_u64 v[200:201], v[186:187], 0, s[96:97]
	global_load_dwordx4 v[144:147], v[198:199], off
	global_load_dwordx4 v[148:151], v[198:199], off offset:256
	global_load_dwordx4 v[152:155], v[200:201], off
	global_load_dwordx4 v[156:159], v[200:201], off offset:256
	v_mov_b32_e32 v0, 0
	v_mov_b32_e32 v1, 0
	v_mov_b32_e32 v2, 0
	v_mov_b32_e32 v3, 0
	v_mov_b32_e32 v4, 0
	v_mov_b32_e32 v5, 0
	v_mov_b32_e32 v6, 0
	v_mov_b32_e32 v7, 0
	v_mov_b32_e32 v8, 0
	v_mov_b32_e32 v9, 0
	v_mov_b32_e32 v10, 0
	v_mov_b32_e32 v11, 0
	v_mov_b32_e32 v12, 0
	v_mov_b32_e32 v13, 0
	v_mov_b32_e32 v14, 0
	v_mov_b32_e32 v15, 0
	v_mov_b32_e32 v16, 0
	v_mov_b32_e32 v17, 0
	v_mov_b32_e32 v18, 0
	v_mov_b32_e32 v19, 0
	v_mov_b32_e32 v20, 0
	v_mov_b32_e32 v21, 0
	v_mov_b32_e32 v22, 0
	v_mov_b32_e32 v23, 0
	v_mov_b32_e32 v24, 0
	v_mov_b32_e32 v25, 0
	v_mov_b32_e32 v26, 0
	v_mov_b32_e32 v27, 0
	v_mov_b32_e32 v28, 0
	v_mov_b32_e32 v29, 0
	v_mov_b32_e32 v30, 0
	v_mov_b32_e32 v31, 0
	v_mov_b32_e32 v32, 0
	v_mov_b32_e32 v33, 0
	v_mov_b32_e32 v34, 0
	v_mov_b32_e32 v35, 0
	v_mov_b32_e32 v36, 0
	v_mov_b32_e32 v37, 0
	v_mov_b32_e32 v38, 0
	v_mov_b32_e32 v39, 0
	v_mov_b32_e32 v40, 0
	v_mov_b32_e32 v41, 0
	v_mov_b32_e32 v42, 0
	v_mov_b32_e32 v43, 0
	v_mov_b32_e32 v44, 0
	v_mov_b32_e32 v45, 0
	v_mov_b32_e32 v46, 0
	v_mov_b32_e32 v47, 0
	v_mov_b32_e32 v48, 0
	v_mov_b32_e32 v49, 0
	v_mov_b32_e32 v50, 0
	v_mov_b32_e32 v51, 0
	v_mov_b32_e32 v52, 0
	v_mov_b32_e32 v53, 0
	v_mov_b32_e32 v54, 0
	v_mov_b32_e32 v55, 0
	v_mov_b32_e32 v56, 0
	v_mov_b32_e32 v57, 0
	v_mov_b32_e32 v58, 0
	v_mov_b32_e32 v59, 0
	v_mov_b32_e32 v60, 0
	v_mov_b32_e32 v61, 0
	v_mov_b32_e32 v62, 0
	v_mov_b32_e32 v63, 0
	v_mov_b32_e32 v64, 0
	v_mov_b32_e32 v65, 0
	v_mov_b32_e32 v66, 0
	v_mov_b32_e32 v67, 0
	v_mov_b32_e32 v68, 0
	v_mov_b32_e32 v69, 0
	v_mov_b32_e32 v70, 0
	v_mov_b32_e32 v71, 0
	v_mov_b32_e32 v72, 0
	v_mov_b32_e32 v73, 0
	v_mov_b32_e32 v74, 0
	v_mov_b32_e32 v75, 0
	v_mov_b32_e32 v76, 0
	v_mov_b32_e32 v77, 0
	v_mov_b32_e32 v78, 0
	v_mov_b32_e32 v79, 0
	v_mov_b32_e32 v80, 0
	v_mov_b32_e32 v81, 0
	v_mov_b32_e32 v82, 0
	v_mov_b32_e32 v83, 0
	v_mov_b32_e32 v84, 0
	v_mov_b32_e32 v85, 0
	v_mov_b32_e32 v86, 0
	v_mov_b32_e32 v87, 0
	v_mov_b32_e32 v88, 0
	v_mov_b32_e32 v89, 0
	v_mov_b32_e32 v90, 0
	v_mov_b32_e32 v91, 0
	v_mov_b32_e32 v92, 0
	v_mov_b32_e32 v93, 0
	v_mov_b32_e32 v94, 0
	v_mov_b32_e32 v95, 0
	v_mov_b32_e32 v96, 0
	v_mov_b32_e32 v97, 0
	v_mov_b32_e32 v98, 0
	v_mov_b32_e32 v99, 0
	v_mov_b32_e32 v100, 0
	v_mov_b32_e32 v101, 0
	v_mov_b32_e32 v102, 0
	v_mov_b32_e32 v103, 0
	v_mov_b32_e32 v104, 0
	v_mov_b32_e32 v105, 0
	v_mov_b32_e32 v106, 0
	v_mov_b32_e32 v107, 0
	v_mov_b32_e32 v108, 0
	v_mov_b32_e32 v109, 0
	v_mov_b32_e32 v110, 0
	v_mov_b32_e32 v111, 0
	v_mov_b32_e32 v112, 0
	v_mov_b32_e32 v113, 0
	v_mov_b32_e32 v114, 0
	v_mov_b32_e32 v115, 0
	v_mov_b32_e32 v116, 0
	v_mov_b32_e32 v117, 0
	v_mov_b32_e32 v118, 0
	v_mov_b32_e32 v119, 0
	v_mov_b32_e32 v120, 0
	v_mov_b32_e32 v121, 0
	v_mov_b32_e32 v122, 0
	v_mov_b32_e32 v123, 0
	v_mov_b32_e32 v124, 0
	v_mov_b32_e32 v125, 0
	v_mov_b32_e32 v126, 0
	v_mov_b32_e32 v127, 0
	s_mov_b32 s1, 0
	s_waitcnt vmcnt(4)
	s_barrier

.LBB0_923:
	s_ashr_i32 s2, s4, 31
	s_lshr_b32 s2, s2, 26
	s_add_i32 s2, s4, s2
	s_ashr_i32 s3, s2, 6
	s_lshl_b32 s3, s3, 3
	s_sub_i32 s8, s25, s3
	s_min_i32 s8, s8, 8
	s_abs_i32 s9, s8
	v_cvt_f32_u32_e32 v0, s9
	s_sub_i32 s12, 0, s9
	s_andn2_b32 s2, s2, 63
	s_sub_i32 s10, s4, s2
	v_rcp_iflag_f32_e32 v0, v0
	s_abs_i32 s2, s10
	s_xor_b32 s11, s10, s8
	s_ashr_i32 s11, s11, 31
	v_mul_f32_e32 v0, 0x4f7ffffe, v0
	v_cvt_u32_f32_e32 v0, v0
	v_mov_b32_e32 v181, v179
	v_readfirstlane_b32 s13, v0
	s_mul_i32 s12, s12, s13
	s_mul_hi_u32 s12, s13, s12
	s_add_i32 s13, s13, s12
	s_mul_hi_u32 s12, s2, s13
	s_mul_i32 s13, s12, s9
	s_sub_i32 s2, s2, s13
	s_add_i32 s14, s12, 1
	s_sub_i32 s13, s2, s9
	s_cmp_ge_u32 s2, s9
	s_cselect_b32 s12, s14, s12
	s_cselect_b32 s2, s13, s2
	s_add_i32 s13, s12, 1
	s_cmp_ge_u32 s2, s9
	s_cselect_b32 s2, s13, s12
	s_xor_b32 s2, s2, s11
	s_sub_i32 s2, s2, s11
	s_mul_i32 s8, s8, s2
	s_add_i32 s3, s3, s7
	s_sub_i32 s8, s10, s8
	v_ashrrev_i32_e32 v237, 6, v181
	s_add_i32 s8, s3, s8
	v_lshlrev_b32_e32 v0, 1, v237
	v_lshl_add_u32 v0, s8, 3, v0
	v_ashrrev_i32_e32 v1, 31, v0
	v_bfe_u32 v183, v181, 5, 1
	v_lshlrev_b64 v[0:1], 16, v[0:1]
	v_and_b32_e32 v238, 31, v181
	v_lshl_add_u64 v[0:1], s[64:65], 0, v[0:1]
	v_lshlrev_b32_e32 v176, 9, v183
	s_ashr_i32 s3, s2, 31
	v_lshl_add_u64 v[0:1], v[0:1], 0, v[176:177]
	v_lshlrev_b32_e32 v176, 4, v238
	v_ashrrev_i32_e32 v40, 2, v181
	s_lshl_b64 s[10:11], s[2:3], 18
	v_lshl_add_u64 v[184:185], v[0:1], 0, v[176:177]
	s_add_u32 s10, s5, s10
	v_lshlrev_b32_e32 v0, 5, v40
	s_addc_u32 s11, s6, s11
	v_ashrrev_i32_e32 v1, 31, v0
	v_lshlrev_b32_e32 v2, 4, v181
	v_lshl_add_u64 v[0:1], v[0:1], 1, s[10:11]
	v_and_b32_e32 v176, 48, v2
	v_lshl_add_u64 v[186:187], v[0:1], 0, v[176:177]
	s_movk_i32 s3, 0x2000
	v_add_co_u32_e32 v36, vcc, s3, v186
	v_mul_u32_u24_e32 v38, 40, v238
	s_nop 0
	v_addc_co_u32_e32 v37, vcc, 0, v187, vcc
	v_lshlrev_b32_e32 v39, 4, v183
	v_lshl_add_u32 v240, v38, 1, v39
	v_add_co_u32_e32 v38, vcc, s41, v184
	s_movk_i32 s9, 0x50
	s_nop 0
	v_addc_co_u32_e32 v39, vcc, 0, v185, vcc
	v_and_b32_e32 v239, 63, v181
	v_lshrrev_b32_e32 v176, 6, v181
	v_lshlrev_b32_e32 v247, 11, v176
	s_nop 0
	v_readfirstlane_b32 vcc_lo, v247
	v_bfe_u32 v247, v181, 4, 2
	v_lshlrev_b32_e32 v247, 1, v247
	v_mov_b32_e32 v176, 0x78
	v_lshrrev_b32_e32 v247, v247, v176
	v_and_b32_e32 v247, 3, v247
	v_and_b32_e32 v246, 3, v181
	v_xor_b32_e32 v247, v247, v246
	v_lshlrev_b32_e32 v247, 4, v247
	v_and_b32_e32 v188, 0xffffffcf, v186
	v_or_b32_e32 v188, v188, v247
	v_mov_b32_e32 v189, v187
	v_lshrrev_b32_e32 v176, 6, v181
	v_lshlrev_b32_e32 v176, 10, v176
	v_lshl_add_u64 v[188:189], v[188:189], 0, v[176:177]
	v_bfe_u32 v247, v181, 4, 1
	v_lshlrev_b32_e32 v176, 9, v183
	v_lshl_add_u32 v176, v247, 8, v176
	v_lshl_add_u64 v[184:185], v[184:185], 0, v[176:177]
	v_mov_b32_e32 v176, s41
	v_lshl_add_u64 v[186:187], v[184:185], 0, v[176:177]
	v_mov_b32_e32 v176, 0x78
	v_bfe_u32 v247, v181, 2, 2
	v_lshlrev_b32_e32 v247, 1, v247
	v_lshrrev_b32_e32 v247, v247, v176
	v_and_b32_e32 v247, 3, v247
	v_bfe_u32 v246, v181, 4, 2
	v_xor_b32_e32 v247, v247, v246
	v_lshlrev_b32_e32 v247, 4, v247
	v_and_b32_e32 v246, 15, v181
	v_lshl_add_u32 v246, v246, 6, v247
	s_mov_b32 s96, 0
	s_mov_b32 m0, vcc_lo
	v_lshl_add_u64 v[160:161], v[188:189], 0, s[96:97]
	global_load_lds_dwordx4 v[160:161], off
	global_load_lds_dwordx4 v[160:161], off offset:1024
	s_mov_b32 s96, 0
	v_lshl_add_u64 v[248:249], v[184:185], 0, s[96:97]
	v_lshl_add_u64 v[250:251], v[186:187], 0, s[96:97]
	global_load_dwordx4 v[128:131], v[248:249], off
	global_load_dwordx4 v[132:135], v[248:249], off offset:256
	global_load_dwordx4 v[136:139], v[250:251], off
	global_load_dwordx4 v[140:143], v[250:251], off offset:256
	s_movk_i32 s96, 0x2000
	s_add_i32 m0, vcc_lo, 8192
	v_lshl_add_u64 v[160:161], v[188:189], 0, s[96:97]
	global_load_lds_dwordx4 v[160:161], off
	global_load_lds_dwordx4 v[160:161], off offset:1024
	s_movk_i32 s96, 0x800
	v_lshl_add_u64 v[248:249], v[184:185], 0, s[96:97]
	v_lshl_add_u64 v[250:251], v[186:187], 0, s[96:97]
	global_load_dwordx4 v[144:147], v[248:249], off
	global_load_dwordx4 v[148:151], v[248:249], off offset:256
	global_load_dwordx4 v[152:155], v[250:251], off
	global_load_dwordx4 v[156:159], v[250:251], off offset:256
	v_mov_b32_e32 v0, 0
	v_mov_b32_e32 v1, 0
	v_mov_b32_e32 v2, 0
	v_mov_b32_e32 v3, 0
	v_mov_b32_e32 v4, 0
	v_mov_b32_e32 v5, 0
	v_mov_b32_e32 v6, 0
	v_mov_b32_e32 v7, 0
	v_mov_b32_e32 v8, 0
	v_mov_b32_e32 v9, 0
	v_mov_b32_e32 v10, 0
	v_mov_b32_e32 v11, 0
	v_mov_b32_e32 v12, 0
	v_mov_b32_e32 v13, 0
	v_mov_b32_e32 v14, 0
	v_mov_b32_e32 v15, 0
	v_mov_b32_e32 v16, 0
	v_mov_b32_e32 v17, 0
	v_mov_b32_e32 v18, 0
	v_mov_b32_e32 v19, 0
	v_mov_b32_e32 v20, 0
	v_mov_b32_e32 v21, 0
	v_mov_b32_e32 v22, 0
	v_mov_b32_e32 v23, 0
	v_mov_b32_e32 v24, 0
	v_mov_b32_e32 v25, 0
	v_mov_b32_e32 v26, 0
	v_mov_b32_e32 v27, 0
	v_mov_b32_e32 v28, 0
	v_mov_b32_e32 v29, 0
	v_mov_b32_e32 v30, 0
	v_mov_b32_e32 v31, 0
	v_mov_b32_e32 v32, 0
	v_mov_b32_e32 v33, 0
	v_mov_b32_e32 v34, 0
	v_mov_b32_e32 v35, 0
	v_mov_b32_e32 v36, 0
	v_mov_b32_e32 v37, 0
	v_mov_b32_e32 v38, 0
	v_mov_b32_e32 v39, 0
	v_mov_b32_e32 v40, 0
	v_mov_b32_e32 v41, 0
	v_mov_b32_e32 v42, 0
	v_mov_b32_e32 v43, 0
	v_mov_b32_e32 v44, 0
	v_mov_b32_e32 v45, 0
	v_mov_b32_e32 v46, 0
	v_mov_b32_e32 v47, 0
	v_mov_b32_e32 v48, 0
	v_mov_b32_e32 v49, 0
	v_mov_b32_e32 v50, 0
	v_mov_b32_e32 v51, 0
	v_mov_b32_e32 v52, 0
	v_mov_b32_e32 v53, 0
	v_mov_b32_e32 v54, 0
	v_mov_b32_e32 v55, 0
	v_mov_b32_e32 v56, 0
	v_mov_b32_e32 v57, 0
	v_mov_b32_e32 v58, 0
	v_mov_b32_e32 v59, 0
	v_mov_b32_e32 v60, 0
	v_mov_b32_e32 v61, 0
	v_mov_b32_e32 v62, 0
	v_mov_b32_e32 v63, 0
	v_mov_b32_e32 v64, 0
	v_mov_b32_e32 v65, 0
	v_mov_b32_e32 v66, 0
	v_mov_b32_e32 v67, 0
	v_mov_b32_e32 v68, 0
	v_mov_b32_e32 v69, 0
	v_mov_b32_e32 v70, 0
	v_mov_b32_e32 v71, 0
	v_mov_b32_e32 v72, 0
	v_mov_b32_e32 v73, 0
	v_mov_b32_e32 v74, 0
	v_mov_b32_e32 v75, 0
	v_mov_b32_e32 v76, 0
	v_mov_b32_e32 v77, 0
	v_mov_b32_e32 v78, 0
	v_mov_b32_e32 v79, 0
	v_mov_b32_e32 v80, 0
	v_mov_b32_e32 v81, 0
	v_mov_b32_e32 v82, 0
	v_mov_b32_e32 v83, 0
	v_mov_b32_e32 v84, 0
	v_mov_b32_e32 v85, 0
	v_mov_b32_e32 v86, 0
	v_mov_b32_e32 v87, 0
	v_mov_b32_e32 v88, 0
	v_mov_b32_e32 v89, 0
	v_mov_b32_e32 v90, 0
	v_mov_b32_e32 v91, 0
	v_mov_b32_e32 v92, 0
	v_mov_b32_e32 v93, 0
	v_mov_b32_e32 v94, 0
	v_mov_b32_e32 v95, 0
	v_mov_b32_e32 v96, 0
	v_mov_b32_e32 v97, 0
	v_mov_b32_e32 v98, 0
	v_mov_b32_e32 v99, 0
	v_mov_b32_e32 v100, 0
	v_mov_b32_e32 v101, 0
	v_mov_b32_e32 v102, 0
	v_mov_b32_e32 v103, 0
	v_mov_b32_e32 v104, 0
	v_mov_b32_e32 v105, 0
	v_mov_b32_e32 v106, 0
	v_mov_b32_e32 v107, 0
	v_mov_b32_e32 v108, 0
	v_mov_b32_e32 v109, 0
	v_mov_b32_e32 v110, 0
	v_mov_b32_e32 v111, 0
	v_mov_b32_e32 v112, 0
	v_mov_b32_e32 v113, 0
	v_mov_b32_e32 v114, 0
	v_mov_b32_e32 v115, 0
	v_mov_b32_e32 v116, 0
	v_mov_b32_e32 v117, 0
	v_mov_b32_e32 v118, 0
	v_mov_b32_e32 v119, 0
	v_mov_b32_e32 v120, 0
	v_mov_b32_e32 v121, 0
	v_mov_b32_e32 v122, 0
	v_mov_b32_e32 v123, 0
	v_mov_b32_e32 v124, 0
	v_mov_b32_e32 v125, 0
	v_mov_b32_e32 v126, 0
	v_mov_b32_e32 v127, 0
	s_mov_b32 s3, 0
	s_waitcnt vmcnt(4)
	s_barrier

.LBB0_1029:
	s_or_b64 exec, exec, s[0:1]
	v_readlane_b32 s0, v253, 0
	s_waitcnt lgkmcnt(0)
	s_barrier
	s_ashr_i32 s2, s0, 3
	s_mul_i32 s3, s25, 44
	s_cmp_ge_i32 s2, s3
	s_cbranch_scc1 .LBB0_1034
	v_readlane_b32 s4, v254, 41
	s_mul_i32 s1, s4, 0xb00000
	v_readlane_b32 s5, v254, 42
	s_add_u32 s4, s52, s1
	s_addc_u32 s5, s53, 0
	s_and_b32 s6, s0, 7
	s_mul_i32 s6, s6, s25
	s_mov_b32 s100, 0
.LBB0_1031:
	s_mul_hi_i32 s0, s2, 0x2e8ba2e9
	s_lshr_b32 s1, s0, 31
	s_ashr_i32 s0, s0, 6
	s_add_i32 s0, s0, s1
	s_lshl_b32 s1, s0, 3
	s_sub_i32 s7, s25, s1
	s_min_i32 s7, s7, 8
	s_abs_i32 s8, s7
	v_cvt_f32_u32_e32 v0, s8
	s_sub_i32 s11, 0, s8
	s_mulk_i32 s0, 0xfea0
	s_add_i32 s9, s0, s2
	v_rcp_iflag_f32_e32 v0, v0
	s_abs_i32 s0, s9
	s_xor_b32 s10, s9, s7
	s_ashr_i32 s10, s10, 31
	v_mul_f32_e32 v0, 0x4f7ffffe, v0
	v_cvt_u32_f32_e32 v0, v0
	v_mov_b32_e32 v237, v179
	v_readfirstlane_b32 s12, v0
	s_mul_i32 s11, s11, s12
	s_mul_hi_u32 s11, s12, s11
	s_add_i32 s12, s12, s11
	s_mul_hi_u32 s11, s0, s12
	s_mul_i32 s12, s11, s8
	s_sub_i32 s0, s0, s12
	s_add_i32 s13, s11, 1
	s_sub_i32 s12, s0, s8
	s_cmp_ge_u32 s0, s8
	s_cselect_b32 s11, s13, s11
	s_cselect_b32 s0, s12, s0
	s_add_i32 s12, s11, 1
	s_cmp_ge_u32 s0, s8
	s_cselect_b32 s0, s12, s11
	s_xor_b32 s0, s0, s10
	s_sub_i32 s0, s0, s10
	s_mul_i32 s7, s7, s0
	s_sub_i32 s7, s9, s7
	s_add_i32 s1, s1, s6
	v_ashrrev_i32_e32 v238, 6, v237
	s_add_i32 s7, s1, s7
	v_lshlrev_b32_e32 v0, 1, v238
	v_lshl_add_u32 v0, s7, 3, v0
	v_ashrrev_i32_e32 v1, 31, v0
	v_bfe_u32 v183, v237, 5, 1
	v_lshlrev_b64 v[0:1], 16, v[0:1]
	v_and_b32_e32 v239, 31, v237
	v_lshl_add_u64 v[0:1], s[64:65], 0, v[0:1]
	v_lshlrev_b32_e32 v176, 9, v183
	s_ashr_i32 s1, s0, 31
	v_lshl_add_u64 v[0:1], v[0:1], 0, v[176:177]
	v_lshlrev_b32_e32 v176, 4, v239
	v_ashrrev_i32_e32 v38, 2, v237
	s_lshl_b64 s[8:9], s[0:1], 18
	v_lshl_add_u64 v[184:185], v[0:1], 0, v[176:177]
	s_add_u32 s8, s4, s8
	v_lshlrev_b32_e32 v0, 5, v38
	v_lshlrev_b32_e32 v2, 3, v237
	s_addc_u32 s9, s5, s9
	v_ashrrev_i32_e32 v1, 31, v0
	v_and_b32_e32 v181, 24, v2
	v_lshl_add_u64 v[0:1], v[0:1], 1, s[8:9]
	v_lshlrev_b32_e32 v176, 1, v181
	v_lshl_add_u64 v[186:187], v[0:1], 0, v[176:177]
	s_movk_i32 s1, 0x2000
	v_add_co_u32_e32 v34, vcc, s1, v186
	v_mul_u32_u24_e32 v36, 40, v239
	s_nop 0
	v_addc_co_u32_e32 v35, vcc, 0, v187, vcc
	v_lshlrev_b32_e32 v37, 4, v183
	v_lshl_add_u32 v241, v36, 1, v37
	v_add_co_u32_e32 v36, vcc, s41, v184
	s_movk_i32 s8, 0x50
	s_nop 0
	v_addc_co_u32_e32 v37, vcc, 0, v185, vcc
	v_mad_u64_u32 v[188:189], s[8:9], v38, s8, v[176:177]
	v_and_b32_e32 v240, 63, v237
	v_lshrrev_b32_e32 v176, 6, v237
	v_lshlrev_b32_e32 v247, 11, v176
	s_nop 0
	v_readfirstlane_b32 vcc_lo, v247
	s_add_i32 vcc_lo, vcc_lo, 36864
	s_cmp_eq_u32 s100, 1
	s_cbranch_scc1 .Lg16_gu_fast
	v_bfe_u32 v247, v237, 4, 2
	v_lshlrev_b32_e32 v247, 1, v247
	v_mov_b32_e32 v176, 0x78
	v_lshrrev_b32_e32 v247, v247, v176
	v_and_b32_e32 v247, 3, v247
	v_and_b32_e32 v174, 3, v237
	v_xor_b32_e32 v247, v247, v174
	v_lshlrev_b32_e32 v247, 4, v247
	v_and_b32_e32 v172, 0xffffffcf, v186
	v_or_b32_e32 v172, v172, v247
	v_mov_b32_e32 v173, v187
	v_lshrrev_b32_e32 v176, 6, v237
	v_lshlrev_b32_e32 v176, 10, v176
	v_lshl_add_u64 v[172:173], v[172:173], 0, v[176:177]
	v_bfe_u32 v247, v237, 4, 1
	v_lshlrev_b32_e32 v176, 9, v183
	v_lshl_add_u32 v176, v247, 8, v176
	v_lshl_add_u64 v[168:169], v[184:185], 0, v[176:177]
	v_mov_b32_e32 v176, s41
	v_lshl_add_u64 v[170:171], v[168:169], 0, v[176:177]
	v_mov_b32_e32 v176, 0x78
	v_bfe_u32 v247, v237, 2, 2
	v_lshlrev_b32_e32 v247, 1, v247
	v_lshrrev_b32_e32 v247, v247, v176
	v_and_b32_e32 v247, 3, v247
	v_bfe_u32 v174, v237, 4, 2
	v_xor_b32_e32 v247, v247, v174
	v_lshlrev_b32_e32 v247, 4, v247
	v_and_b32_e32 v174, 15, v237
	v_lshl_add_u32 v174, v174, 6, v247
	v_add_u32_e32 v174, 36864, v174
	s_mov_b32 s96, 0
	s_mov_b32 m0, vcc_lo
	v_lshl_add_u64 v[128:129], v[172:173], 0, s[96:97]
	global_load_lds_dwordx4 v[128:129], off
	global_load_lds_dwordx4 v[128:129], off offset:1024
	s_mov_b32 s96, 0
	v_lshl_add_u64 v[248:249], v[168:169], 0, s[96:97]
	v_lshl_add_u64 v[250:251], v[170:171], 0, s[96:97]
	global_load_dwordx4 v[136:139], v[248:249], off
	global_load_dwordx4 v[140:143], v[248:249], off offset:256
	global_load_dwordx4 v[144:147], v[250:251], off
	global_load_dwordx4 v[148:151], v[250:251], off offset:256
	s_movk_i32 s96, 0x2000
	s_add_i32 m0, vcc_lo, 8192
	v_lshl_add_u64 v[128:129], v[172:173], 0, s[96:97]
	global_load_lds_dwordx4 v[128:129], off
	global_load_lds_dwordx4 v[128:129], off offset:1024
	s_movk_i32 s96, 0x800
	v_lshl_add_u64 v[248:249], v[168:169], 0, s[96:97]
	v_lshl_add_u64 v[250:251], v[170:171], 0, s[96:97]
	global_load_dwordx4 v[152:155], v[248:249], off
	global_load_dwordx4 v[156:159], v[248:249], off offset:256
	global_load_dwordx4 v[160:163], v[250:251], off
	global_load_dwordx4 v[164:167], v[250:251], off offset:256
	v_mov_b32_e32 v0, 0
	v_mov_b32_e32 v1, 0
	v_mov_b32_e32 v2, 0
	v_mov_b32_e32 v3, 0
	v_mov_b32_e32 v4, 0
	v_mov_b32_e32 v5, 0
	v_mov_b32_e32 v6, 0
	v_mov_b32_e32 v7, 0
	v_mov_b32_e32 v8, 0
	v_mov_b32_e32 v9, 0
	v_mov_b32_e32 v10, 0
	v_mov_b32_e32 v11, 0
	v_mov_b32_e32 v12, 0
	v_mov_b32_e32 v13, 0
	v_mov_b32_e32 v14, 0
	v_mov_b32_e32 v15, 0
	v_mov_b32_e32 v16, 0
	v_mov_b32_e32 v17, 0
	v_mov_b32_e32 v18, 0
	v_mov_b32_e32 v19, 0
	v_mov_b32_e32 v20, 0
	v_mov_b32_e32 v21, 0
	v_mov_b32_e32 v22, 0
	v_mov_b32_e32 v23, 0
	v_mov_b32_e32 v24, 0
	v_mov_b32_e32 v25, 0
	v_mov_b32_e32 v26, 0
	v_mov_b32_e32 v27, 0
	v_mov_b32_e32 v28, 0
	v_mov_b32_e32 v29, 0
	v_mov_b32_e32 v30, 0
	v_mov_b32_e32 v31, 0
	v_mov_b32_e32 v32, 0
	v_mov_b32_e32 v33, 0
	v_mov_b32_e32 v34, 0
	v_mov_b32_e32 v35, 0
	v_mov_b32_e32 v36, 0
	v_mov_b32_e32 v37, 0
	v_mov_b32_e32 v38, 0
	v_mov_b32_e32 v39, 0
	v_mov_b32_e32 v40, 0
	v_mov_b32_e32 v41, 0
	v_mov_b32_e32 v42, 0
	v_mov_b32_e32 v43, 0
	v_mov_b32_e32 v44, 0
	v_mov_b32_e32 v45, 0
	v_mov_b32_e32 v46, 0
	v_mov_b32_e32 v47, 0
	v_mov_b32_e32 v48, 0
	v_mov_b32_e32 v49, 0
	v_mov_b32_e32 v50, 0
	v_mov_b32_e32 v51, 0
	v_mov_b32_e32 v52, 0
	v_mov_b32_e32 v53, 0
	v_mov_b32_e32 v54, 0
	v_mov_b32_e32 v55, 0
	v_mov_b32_e32 v56, 0
	v_mov_b32_e32 v57, 0
	v_mov_b32_e32 v58, 0
	v_mov_b32_e32 v59, 0
	v_mov_b32_e32 v60, 0
	v_mov_b32_e32 v61, 0
	v_mov_b32_e32 v62, 0
	v_mov_b32_e32 v63, 0
	v_mov_b32_e32 v64, 0
	v_mov_b32_e32 v65, 0
	v_mov_b32_e32 v66, 0
	v_mov_b32_e32 v67, 0
	v_mov_b32_e32 v68, 0
	v_mov_b32_e32 v69, 0
	v_mov_b32_e32 v70, 0
	v_mov_b32_e32 v71, 0
	v_mov_b32_e32 v72, 0
	v_mov_b32_e32 v73, 0
	v_mov_b32_e32 v74, 0
	v_mov_b32_e32 v75, 0
	v_mov_b32_e32 v76, 0
	v_mov_b32_e32 v77, 0
	v_mov_b32_e32 v78, 0
	v_mov_b32_e32 v79, 0
	v_mov_b32_e32 v80, 0
	v_mov_b32_e32 v81, 0
	v_mov_b32_e32 v82, 0
	v_mov_b32_e32 v83, 0
	v_mov_b32_e32 v84, 0
	v_mov_b32_e32 v85, 0
	v_mov_b32_e32 v86, 0
	v_mov_b32_e32 v87, 0
	v_mov_b32_e32 v88, 0
	v_mov_b32_e32 v89, 0
	v_mov_b32_e32 v90, 0
	v_mov_b32_e32 v91, 0
	v_mov_b32_e32 v92, 0
	v_mov_b32_e32 v93, 0
	v_mov_b32_e32 v94, 0
	v_mov_b32_e32 v95, 0
	v_mov_b32_e32 v96, 0
	v_mov_b32_e32 v97, 0
	v_mov_b32_e32 v98, 0
	v_mov_b32_e32 v99, 0
	v_mov_b32_e32 v100, 0
	v_mov_b32_e32 v101, 0
	v_mov_b32_e32 v102, 0
	v_mov_b32_e32 v103, 0
	v_mov_b32_e32 v104, 0
	v_mov_b32_e32 v105, 0
	v_mov_b32_e32 v106, 0
	v_mov_b32_e32 v107, 0
	v_mov_b32_e32 v108, 0
	v_mov_b32_e32 v109, 0
	v_mov_b32_e32 v110, 0
	v_mov_b32_e32 v111, 0
	v_mov_b32_e32 v112, 0
	v_mov_b32_e32 v113, 0
	v_mov_b32_e32 v114, 0
	v_mov_b32_e32 v115, 0
	v_mov_b32_e32 v116, 0
	v_mov_b32_e32 v117, 0
	v_mov_b32_e32 v118, 0
	v_mov_b32_e32 v119, 0
	v_mov_b32_e32 v120, 0
	v_mov_b32_e32 v121, 0
	v_mov_b32_e32 v122, 0
	v_mov_b32_e32 v123, 0
	v_mov_b32_e32 v124, 0
	v_mov_b32_e32 v125, 0
	v_mov_b32_e32 v126, 0
	v_mov_b32_e32 v127, 0
	s_mov_b32 s1, 0
	s_waitcnt vmcnt(4)
	s_barrier
	s_branch .Lg16_gu_go
.Lg16_gu_fast:
	v_mov_b32_e32 v0, 0
	v_mov_b32_e32 v1, 0
	v_mov_b32_e32 v2, 0
	v_mov_b32_e32 v3, 0
	v_mov_b32_e32 v4, 0
	v_mov_b32_e32 v5, 0
	v_mov_b32_e32 v6, 0
	v_mov_b32_e32 v7, 0
	v_mov_b32_e32 v8, 0
	v_mov_b32_e32 v9, 0
	v_mov_b32_e32 v10, 0
	v_mov_b32_e32 v11, 0
	v_mov_b32_e32 v12, 0
	v_mov_b32_e32 v13, 0
	v_mov_b32_e32 v14, 0
	v_mov_b32_e32 v15, 0
	v_mov_b32_e32 v16, 0
	v_mov_b32_e32 v17, 0
	v_mov_b32_e32 v18, 0
	v_mov_b32_e32 v19, 0
	v_mov_b32_e32 v20, 0
	v_mov_b32_e32 v21, 0
	v_mov_b32_e32 v22, 0
	v_mov_b32_e32 v23, 0
	v_mov_b32_e32 v24, 0
	v_mov_b32_e32 v25, 0
	v_mov_b32_e32 v26, 0
	v_mov_b32_e32 v27, 0
	v_mov_b32_e32 v28, 0
	v_mov_b32_e32 v29, 0
	v_mov_b32_e32 v30, 0
	v_mov_b32_e32 v31, 0
	v_mov_b32_e32 v32, 0
	v_mov_b32_e32 v33, 0
	v_mov_b32_e32 v34, 0
	v_mov_b32_e32 v35, 0
	v_mov_b32_e32 v36, 0
	v_mov_b32_e32 v37, 0
	v_mov_b32_e32 v38, 0
	v_mov_b32_e32 v39, 0
	v_mov_b32_e32 v40, 0
	v_mov_b32_e32 v41, 0
	v_mov_b32_e32 v42, 0
	v_mov_b32_e32 v43, 0
	v_mov_b32_e32 v44, 0
	v_mov_b32_e32 v45, 0
	v_mov_b32_e32 v46, 0
	v_mov_b32_e32 v47, 0
	v_mov_b32_e32 v48, 0
	v_mov_b32_e32 v49, 0
	v_mov_b32_e32 v50, 0
	v_mov_b32_e32 v51, 0
	v_mov_b32_e32 v52, 0
	v_mov_b32_e32 v53, 0
	v_mov_b32_e32 v54, 0
	v_mov_b32_e32 v55, 0
	v_mov_b32_e32 v56, 0
	v_mov_b32_e32 v57, 0
	v_mov_b32_e32 v58, 0
	v_mov_b32_e32 v59, 0
	v_mov_b32_e32 v60, 0
	v_mov_b32_e32 v61, 0
	v_mov_b32_e32 v62, 0
	v_mov_b32_e32 v63, 0
	v_mov_b32_e32 v64, 0
	v_mov_b32_e32 v65, 0
	v_mov_b32_e32 v66, 0
	v_mov_b32_e32 v67, 0
	v_mov_b32_e32 v68, 0
	v_mov_b32_e32 v69, 0
	v_mov_b32_e32 v70, 0
	v_mov_b32_e32 v71, 0
	v_mov_b32_e32 v72, 0
	v_mov_b32_e32 v73, 0
	v_mov_b32_e32 v74, 0
	v_mov_b32_e32 v75, 0
	v_mov_b32_e32 v76, 0
	v_mov_b32_e32 v77, 0
	v_mov_b32_e32 v78, 0
	v_mov_b32_e32 v79, 0
	v_mov_b32_e32 v80, 0
	v_mov_b32_e32 v81, 0
	v_mov_b32_e32 v82, 0
	v_mov_b32_e32 v83, 0
	v_mov_b32_e32 v84, 0
	v_mov_b32_e32 v85, 0
	v_mov_b32_e32 v86, 0
	v_mov_b32_e32 v87, 0
	v_mov_b32_e32 v88, 0
	v_mov_b32_e32 v89, 0
	v_mov_b32_e32 v90, 0
	v_mov_b32_e32 v91, 0
	v_mov_b32_e32 v92, 0
	v_mov_b32_e32 v93, 0
	v_mov_b32_e32 v94, 0
	v_mov_b32_e32 v95, 0
	v_mov_b32_e32 v96, 0
	v_mov_b32_e32 v97, 0
	v_mov_b32_e32 v98, 0
	v_mov_b32_e32 v99, 0
	v_mov_b32_e32 v100, 0
	v_mov_b32_e32 v101, 0
	v_mov_b32_e32 v102, 0
	v_mov_b32_e32 v103, 0
	v_mov_b32_e32 v104, 0
	v_mov_b32_e32 v105, 0
	v_mov_b32_e32 v106, 0
	v_mov_b32_e32 v107, 0
	v_mov_b32_e32 v108, 0
	v_mov_b32_e32 v109, 0
	v_mov_b32_e32 v110, 0
	v_mov_b32_e32 v111, 0
	v_mov_b32_e32 v112, 0
	v_mov_b32_e32 v113, 0
	v_mov_b32_e32 v114, 0
	v_mov_b32_e32 v115, 0
	v_mov_b32_e32 v116, 0
	v_mov_b32_e32 v117, 0
	v_mov_b32_e32 v118, 0
	v_mov_b32_e32 v119, 0
	v_mov_b32_e32 v120, 0
	v_mov_b32_e32 v121, 0
	v_mov_b32_e32 v122, 0
	v_mov_b32_e32 v123, 0
	v_mov_b32_e32 v124, 0
	v_mov_b32_e32 v125, 0
	v_mov_b32_e32 v126, 0
	v_mov_b32_e32 v127, 0
	s_mov_b32 s1, 0
	s_waitcnt vmcnt(12)
	s_barrier
.Lg16_gu_go:
.Lg16_gu_k:
	s_add_i32 s8, s1, 2
	s_lshl_b32 s96, s8, 13
	s_add_i32 m0, vcc_lo, 16384
	v_lshl_add_u64 v[128:129], v[172:173], 0, s[96:97]
	global_load_lds_dwordx4 v[128:129], off
	global_load_lds_dwordx4 v[128:129], off offset:1024
	ds_read_b128 v[196:199], v174 offset:0
	ds_read_b128 v[200:203], v174 offset:1024
	ds_read_b128 v[204:207], v174 offset:2048
	ds_read_b128 v[242:245], v174 offset:3072
	s_add_i32 s8, s1, 2
	s_lshl_b32 s96, s8, 11
	v_lshl_add_u64 v[248:249], v[168:169], 0, s[96:97]
	v_lshl_add_u64 v[250:251], v[170:171], 0, s[96:97]
	s_waitcnt vmcnt(8) lgkmcnt(3)
	v_mfma_f32_16x16x32_bf16 v[112:115], v[136:139], v[196:199], v[112:115]
	v_mfma_f32_16x16x32_bf16 v[120:123], v[140:143], v[196:199], v[120:123]
	v_mfma_f32_16x16x32_bf16 v[80:83], v[144:147], v[196:199], v[80:83]
	v_mfma_f32_16x16x32_bf16 v[88:91], v[148:151], v[196:199], v[88:91]
	ds_read_b128 v[196:199], v174 offset:4096
	s_waitcnt lgkmcnt(3)
	v_mfma_f32_16x16x32_bf16 v[116:119], v[136:139], v[200:203], v[116:119]
	v_mfma_f32_16x16x32_bf16 v[124:127], v[140:143], v[200:203], v[124:127]
	v_mfma_f32_16x16x32_bf16 v[84:87], v[144:147], v[200:203], v[84:87]
	v_mfma_f32_16x16x32_bf16 v[92:95], v[148:151], v[200:203], v[92:95]
	ds_read_b128 v[200:203], v174 offset:5120
	s_waitcnt lgkmcnt(3)
	v_mfma_f32_16x16x32_bf16 v[96:99], v[136:139], v[204:207], v[96:99]
	v_mfma_f32_16x16x32_bf16 v[104:107], v[140:143], v[204:207], v[104:107]
	v_mfma_f32_16x16x32_bf16 v[64:67], v[144:147], v[204:207], v[64:67]
	v_mfma_f32_16x16x32_bf16 v[72:75], v[148:151], v[204:207], v[72:75]
	ds_read_b128 v[204:207], v174 offset:6144
	s_waitcnt lgkmcnt(3)
	v_mfma_f32_16x16x32_bf16 v[100:103], v[136:139], v[242:245], v[100:103]
	v_mfma_f32_16x16x32_bf16 v[108:111], v[140:143], v[242:245], v[108:111]
	v_mfma_f32_16x16x32_bf16 v[68:71], v[144:147], v[242:245], v[68:71]
	v_mfma_f32_16x16x32_bf16 v[76:79], v[148:151], v[242:245], v[76:79]
	ds_read_b128 v[242:245], v174 offset:7168
	s_waitcnt lgkmcnt(3)
	v_mfma_f32_16x16x32_bf16 v[48:51], v[136:139], v[196:199], v[48:51]
	v_mfma_f32_16x16x32_bf16 v[56:59], v[140:143], v[196:199], v[56:59]
	v_mfma_f32_16x16x32_bf16 v[16:19], v[144:147], v[196:199], v[16:19]
	v_mfma_f32_16x16x32_bf16 v[24:27], v[148:151], v[196:199], v[24:27]
	s_waitcnt lgkmcnt(2)
	v_mfma_f32_16x16x32_bf16 v[52:55], v[136:139], v[200:203], v[52:55]
	v_mfma_f32_16x16x32_bf16 v[60:63], v[140:143], v[200:203], v[60:63]
	v_mfma_f32_16x16x32_bf16 v[20:23], v[144:147], v[200:203], v[20:23]
	v_mfma_f32_16x16x32_bf16 v[28:31], v[148:151], v[200:203], v[28:31]
	s_waitcnt lgkmcnt(1)
	v_mfma_f32_16x16x32_bf16 v[32:35], v[136:139], v[204:207], v[32:35]
	v_mfma_f32_16x16x32_bf16 v[40:43], v[140:143], v[204:207], v[40:43]
	v_mfma_f32_16x16x32_bf16 v[0:3], v[144:147], v[204:207], v[0:3]
	v_mfma_f32_16x16x32_bf16 v[8:11], v[148:151], v[204:207], v[8:11]
	s_waitcnt lgkmcnt(0)
	v_mfma_f32_16x16x32_bf16 v[36:39], v[136:139], v[242:245], v[36:39]
	v_mfma_f32_16x16x32_bf16 v[44:47], v[140:143], v[242:245], v[44:47]
	v_mfma_f32_16x16x32_bf16 v[4:7], v[144:147], v[242:245], v[4:7]
	v_mfma_f32_16x16x32_bf16 v[12:15], v[148:151], v[242:245], v[12:15]
	global_load_dwordx4 v[136:139], v[248:249], off
	global_load_dwordx4 v[140:143], v[248:249], off offset:256
	global_load_dwordx4 v[144:147], v[250:251], off
	global_load_dwordx4 v[148:151], v[250:251], off offset:256
	s_waitcnt vmcnt(10)
	s_barrier
	s_add_i32 s8, s1, 3
	s_lshl_b32 s96, s8, 13
	s_mov_b32 m0, vcc_lo
	v_lshl_add_u64 v[128:129], v[172:173], 0, s[96:97]
	global_load_lds_dwordx4 v[128:129], off
	global_load_lds_dwordx4 v[128:129], off offset:1024
	ds_read_b128 v[196:199], v174 offset:8192
	ds_read_b128 v[200:203], v174 offset:9216
	ds_read_b128 v[204:207], v174 offset:10240
	ds_read_b128 v[242:245], v174 offset:11264
	s_add_i32 s8, s1, 3
	s_lshl_b32 s96, s8, 11
	v_lshl_add_u64 v[248:249], v[168:169], 0, s[96:97]
	v_lshl_add_u64 v[250:251], v[170:171], 0, s[96:97]
	s_waitcnt vmcnt(8) lgkmcnt(3)
	v_mfma_f32_16x16x32_bf16 v[112:115], v[152:155], v[196:199], v[112:115]
	v_mfma_f32_16x16x32_bf16 v[120:123], v[156:159], v[196:199], v[120:123]
	v_mfma_f32_16x16x32_bf16 v[80:83], v[160:163], v[196:199], v[80:83]
	v_mfma_f32_16x16x32_bf16 v[88:91], v[164:167], v[196:199], v[88:91]
	ds_read_b128 v[196:199], v174 offset:12288
	s_waitcnt lgkmcnt(3)
	v_mfma_f32_16x16x32_bf16 v[116:119], v[152:155], v[200:203], v[116:119]
	v_mfma_f32_16x16x32_bf16 v[124:127], v[156:159], v[200:203], v[124:127]
	v_mfma_f32_16x16x32_bf16 v[84:87], v[160:163], v[200:203], v[84:87]
	v_mfma_f32_16x16x32_bf16 v[92:95], v[164:167], v[200:203], v[92:95]
	ds_read_b128 v[200:203], v174 offset:13312
	s_waitcnt lgkmcnt(3)
	v_mfma_f32_16x16x32_bf16 v[96:99], v[152:155], v[204:207], v[96:99]
	v_mfma_f32_16x16x32_bf16 v[104:107], v[156:159], v[204:207], v[104:107]
	v_mfma_f32_16x16x32_bf16 v[64:67], v[160:163], v[204:207], v[64:67]
	v_mfma_f32_16x16x32_bf16 v[72:75], v[164:167], v[204:207], v[72:75]
	ds_read_b128 v[204:207], v174 offset:14336
	s_waitcnt lgkmcnt(3)
	v_mfma_f32_16x16x32_bf16 v[100:103], v[152:155], v[242:245], v[100:103]
	v_mfma_f32_16x16x32_bf16 v[108:111], v[156:159], v[242:245], v[108:111]
	v_mfma_f32_16x16x32_bf16 v[68:71], v[160:163], v[242:245], v[68:71]
	v_mfma_f32_16x16x32_bf16 v[76:79], v[164:167], v[242:245], v[76:79]
	ds_read_b128 v[242:245], v174 offset:15360
	s_waitcnt lgkmcnt(3)
	v_mfma_f32_16x16x32_bf16 v[48:51], v[152:155], v[196:199], v[48:51]
	v_mfma_f32_16x16x32_bf16 v[56:59], v[156:159], v[196:199], v[56:59]
	v_mfma_f32_16x16x32_bf16 v[16:19], v[160:163], v[196:199], v[16:19]
	v_mfma_f32_16x16x32_bf16 v[24:27], v[164:167], v[196:199], v[24:27]
	s_waitcnt lgkmcnt(2)
	v_mfma_f32_16x16x32_bf16 v[52:55], v[152:155], v[200:203], v[52:55]
	v_mfma_f32_16x16x32_bf16 v[60:63], v[156:159], v[200:203], v[60:63]
	v_mfma_f32_16x16x32_bf16 v[20:23], v[160:163], v[200:203], v[20:23]
	v_mfma_f32_16x16x32_bf16 v[28:31], v[164:167], v[200:203], v[28:31]
	s_waitcnt lgkmcnt(1)
	v_mfma_f32_16x16x32_bf16 v[32:35], v[152:155], v[204:207], v[32:35]
	v_mfma_f32_16x16x32_bf16 v[40:43], v[156:159], v[204:207], v[40:43]
	v_mfma_f32_16x16x32_bf16 v[0:3], v[160:163], v[204:207], v[0:3]
	v_mfma_f32_16x16x32_bf16 v[8:11], v[164:167], v[204:207], v[8:11]
	s_waitcnt lgkmcnt(0)
	v_mfma_f32_16x16x32_bf16 v[36:39], v[152:155], v[242:245], v[36:39]
	v_mfma_f32_16x16x32_bf16 v[44:47], v[156:159], v[242:245], v[44:47]
	v_mfma_f32_16x16x32_bf16 v[4:7], v[160:163], v[242:245], v[4:7]
	v_mfma_f32_16x16x32_bf16 v[12:15], v[164:167], v[242:245], v[12:15]
	global_load_dwordx4 v[152:155], v[248:249], off
	global_load_dwordx4 v[156:159], v[248:249], off offset:256
	global_load_dwordx4 v[160:163], v[250:251], off
	global_load_dwordx4 v[164:167], v[250:251], off offset:256
	s_waitcnt vmcnt(10)
	s_barrier
	s_add_i32 s8, s1, 4
	s_lshl_b32 s96, s8, 13
	s_add_i32 m0, vcc_lo, 8192
	v_lshl_add_u64 v[128:129], v[172:173], 0, s[96:97]
	global_load_lds_dwordx4 v[128:129], off
	global_load_lds_dwordx4 v[128:129], off offset:1024
	ds_read_b128 v[196:199], v174 offset:16384
	ds_read_b128 v[200:203], v174 offset:17408
	ds_read_b128 v[204:207], v174 offset:18432
	ds_read_b128 v[242:245], v174 offset:19456
	s_add_i32 s8, s1, 4
	s_lshl_b32 s96, s8, 11
	v_lshl_add_u64 v[248:249], v[168:169], 0, s[96:97]
	v_lshl_add_u64 v[250:251], v[170:171], 0, s[96:97]
	s_waitcnt vmcnt(8) lgkmcnt(3)
	v_mfma_f32_16x16x32_bf16 v[112:115], v[136:139], v[196:199], v[112:115]
	v_mfma_f32_16x16x32_bf16 v[120:123], v[140:143], v[196:199], v[120:123]
	v_mfma_f32_16x16x32_bf16 v[80:83], v[144:147], v[196:199], v[80:83]
	v_mfma_f32_16x16x32_bf16 v[88:91], v[148:151], v[196:199], v[88:91]
	ds_read_b128 v[196:199], v174 offset:20480
	s_waitcnt lgkmcnt(3)
	v_mfma_f32_16x16x32_bf16 v[116:119], v[136:139], v[200:203], v[116:119]
	v_mfma_f32_16x16x32_bf16 v[124:127], v[140:143], v[200:203], v[124:127]
	v_mfma_f32_16x16x32_bf16 v[84:87], v[144:147], v[200:203], v[84:87]
	v_mfma_f32_16x16x32_bf16 v[92:95], v[148:151], v[200:203], v[92:95]
	ds_read_b128 v[200:203], v174 offset:21504
	s_waitcnt lgkmcnt(3)
	v_mfma_f32_16x16x32_bf16 v[96:99], v[136:139], v[204:207], v[96:99]
	v_mfma_f32_16x16x32_bf16 v[104:107], v[140:143], v[204:207], v[104:107]
	v_mfma_f32_16x16x32_bf16 v[64:67], v[144:147], v[204:207], v[64:67]
	v_mfma_f32_16x16x32_bf16 v[72:75], v[148:151], v[204:207], v[72:75]
	ds_read_b128 v[204:207], v174 offset:22528
	s_waitcnt lgkmcnt(3)
	v_mfma_f32_16x16x32_bf16 v[100:103], v[136:139], v[242:245], v[100:103]
	v_mfma_f32_16x16x32_bf16 v[108:111], v[140:143], v[242:245], v[108:111]
	v_mfma_f32_16x16x32_bf16 v[68:71], v[144:147], v[242:245], v[68:71]
	v_mfma_f32_16x16x32_bf16 v[76:79], v[148:151], v[242:245], v[76:79]
	ds_read_b128 v[242:245], v174 offset:23552
	s_waitcnt lgkmcnt(3)
	v_mfma_f32_16x16x32_bf16 v[48:51], v[136:139], v[196:199], v[48:51]
	v_mfma_f32_16x16x32_bf16 v[56:59], v[140:143], v[196:199], v[56:59]
	v_mfma_f32_16x16x32_bf16 v[16:19], v[144:147], v[196:199], v[16:19]
	v_mfma_f32_16x16x32_bf16 v[24:27], v[148:151], v[196:199], v[24:27]
	s_waitcnt lgkmcnt(2)
	v_mfma_f32_16x16x32_bf16 v[52:55], v[136:139], v[200:203], v[52:55]
	v_mfma_f32_16x16x32_bf16 v[60:63], v[140:143], v[200:203], v[60:63]
	v_mfma_f32_16x16x32_bf16 v[20:23], v[144:147], v[200:203], v[20:23]
	v_mfma_f32_16x16x32_bf16 v[28:31], v[148:151], v[200:203], v[28:31]
	s_waitcnt lgkmcnt(1)
	v_mfma_f32_16x16x32_bf16 v[32:35], v[136:139], v[204:207], v[32:35]
	v_mfma_f32_16x16x32_bf16 v[40:43], v[140:143], v[204:207], v[40:43]
	v_mfma_f32_16x16x32_bf16 v[0:3], v[144:147], v[204:207], v[0:3]
	v_mfma_f32_16x16x32_bf16 v[8:11], v[148:151], v[204:207], v[8:11]
	s_waitcnt lgkmcnt(0)
	v_mfma_f32_16x16x32_bf16 v[36:39], v[136:139], v[242:245], v[36:39]
	v_mfma_f32_16x16x32_bf16 v[44:47], v[140:143], v[242:245], v[44:47]
	v_mfma_f32_16x16x32_bf16 v[4:7], v[144:147], v[242:245], v[4:7]
	v_mfma_f32_16x16x32_bf16 v[12:15], v[148:151], v[242:245], v[12:15]
	global_load_dwordx4 v[136:139], v[248:249], off
	global_load_dwordx4 v[140:143], v[248:249], off offset:256
	global_load_dwordx4 v[144:147], v[250:251], off
	global_load_dwordx4 v[148:151], v[250:251], off offset:256
	s_waitcnt vmcnt(10)
	s_barrier
	s_add_i32 s8, s1, 5
	s_lshl_b32 s96, s8, 13
	s_add_i32 m0, vcc_lo, 16384
	v_lshl_add_u64 v[128:129], v[172:173], 0, s[96:97]
	global_load_lds_dwordx4 v[128:129], off
	global_load_lds_dwordx4 v[128:129], off offset:1024
	ds_read_b128 v[196:199], v174 offset:0
	ds_read_b128 v[200:203], v174 offset:1024
	ds_read_b128 v[204:207], v174 offset:2048
	ds_read_b128 v[242:245], v174 offset:3072
	s_add_i32 s8, s1, 5
	s_lshl_b32 s96, s8, 11
	v_lshl_add_u64 v[248:249], v[168:169], 0, s[96:97]
	v_lshl_add_u64 v[250:251], v[170:171], 0, s[96:97]
	s_waitcnt vmcnt(8) lgkmcnt(3)
	v_mfma_f32_16x16x32_bf16 v[112:115], v[152:155], v[196:199], v[112:115]
	v_mfma_f32_16x16x32_bf16 v[120:123], v[156:159], v[196:199], v[120:123]
	v_mfma_f32_16x16x32_bf16 v[80:83], v[160:163], v[196:199], v[80:83]
	v_mfma_f32_16x16x32_bf16 v[88:91], v[164:167], v[196:199], v[88:91]
	ds_read_b128 v[196:199], v174 offset:4096
	s_waitcnt lgkmcnt(3)
	v_mfma_f32_16x16x32_bf16 v[116:119], v[152:155], v[200:203], v[116:119]
	v_mfma_f32_16x16x32_bf16 v[124:127], v[156:159], v[200:203], v[124:127]
	v_mfma_f32_16x16x32_bf16 v[84:87], v[160:163], v[200:203], v[84:87]
	v_mfma_f32_16x16x32_bf16 v[92:95], v[164:167], v[200:203], v[92:95]
	ds_read_b128 v[200:203], v174 offset:5120
	s_waitcnt lgkmcnt(3)
	v_mfma_f32_16x16x32_bf16 v[96:99], v[152:155], v[204:207], v[96:99]
	v_mfma_f32_16x16x32_bf16 v[104:107], v[156:159], v[204:207], v[104:107]
	v_mfma_f32_16x16x32_bf16 v[64:67], v[160:163], v[204:207], v[64:67]
	v_mfma_f32_16x16x32_bf16 v[72:75], v[164:167], v[204:207], v[72:75]
	ds_read_b128 v[204:207], v174 offset:6144
	s_waitcnt lgkmcnt(3)
	v_mfma_f32_16x16x32_bf16 v[100:103], v[152:155], v[242:245], v[100:103]
	v_mfma_f32_16x16x32_bf16 v[108:111], v[156:159], v[242:245], v[108:111]
	v_mfma_f32_16x16x32_bf16 v[68:71], v[160:163], v[242:245], v[68:71]
	v_mfma_f32_16x16x32_bf16 v[76:79], v[164:167], v[242:245], v[76:79]
	ds_read_b128 v[242:245], v174 offset:7168
	s_waitcnt lgkmcnt(3)
	v_mfma_f32_16x16x32_bf16 v[48:51], v[152:155], v[196:199], v[48:51]
	v_mfma_f32_16x16x32_bf16 v[56:59], v[156:159], v[196:199], v[56:59]
	v_mfma_f32_16x16x32_bf16 v[16:19], v[160:163], v[196:199], v[16:19]
	v_mfma_f32_16x16x32_bf16 v[24:27], v[164:167], v[196:199], v[24:27]
	s_waitcnt lgkmcnt(2)
	v_mfma_f32_16x16x32_bf16 v[52:55], v[152:155], v[200:203], v[52:55]
	v_mfma_f32_16x16x32_bf16 v[60:63], v[156:159], v[200:203], v[60:63]
	v_mfma_f32_16x16x32_bf16 v[20:23], v[160:163], v[200:203], v[20:23]
	v_mfma_f32_16x16x32_bf16 v[28:31], v[164:167], v[200:203], v[28:31]
	s_waitcnt lgkmcnt(1)
	v_mfma_f32_16x16x32_bf16 v[32:35], v[152:155], v[204:207], v[32:35]
	v_mfma_f32_16x16x32_bf16 v[40:43], v[156:159], v[204:207], v[40:43]
	v_mfma_f32_16x16x32_bf16 v[0:3], v[160:163], v[204:207], v[0:3]
	v_mfma_f32_16x16x32_bf16 v[8:11], v[164:167], v[204:207], v[8:11]
	s_waitcnt lgkmcnt(0)
	v_mfma_f32_16x16x32_bf16 v[36:39], v[152:155], v[242:245], v[36:39]
	v_mfma_f32_16x16x32_bf16 v[44:47], v[156:159], v[242:245], v[44:47]
	v_mfma_f32_16x16x32_bf16 v[4:7], v[160:163], v[242:245], v[4:7]
	v_mfma_f32_16x16x32_bf16 v[12:15], v[164:167], v[242:245], v[12:15]
	global_load_dwordx4 v[152:155], v[248:249], off
	global_load_dwordx4 v[156:159], v[248:249], off offset:256
	global_load_dwordx4 v[160:163], v[250:251], off
	global_load_dwordx4 v[164:167], v[250:251], off offset:256
	s_waitcnt vmcnt(10)
	s_barrier
	s_add_i32 s8, s1, 6
	s_lshl_b32 s96, s8, 13
	s_mov_b32 m0, vcc_lo
	v_lshl_add_u64 v[128:129], v[172:173], 0, s[96:97]
	global_load_lds_dwordx4 v[128:129], off
	global_load_lds_dwordx4 v[128:129], off offset:1024
	ds_read_b128 v[196:199], v174 offset:8192
	ds_read_b128 v[200:203], v174 offset:9216
	ds_read_b128 v[204:207], v174 offset:10240
	ds_read_b128 v[242:245], v174 offset:11264
	s_add_i32 s8, s1, 6
	s_lshl_b32 s96, s8, 11
	v_lshl_add_u64 v[248:249], v[168:169], 0, s[96:97]
	v_lshl_add_u64 v[250:251], v[170:171], 0, s[96:97]
	s_waitcnt vmcnt(8) lgkmcnt(3)
	v_mfma_f32_16x16x32_bf16 v[112:115], v[136:139], v[196:199], v[112:115]
	v_mfma_f32_16x16x32_bf16 v[120:123], v[140:143], v[196:199], v[120:123]
	v_mfma_f32_16x16x32_bf16 v[80:83], v[144:147], v[196:199], v[80:83]
	v_mfma_f32_16x16x32_bf16 v[88:91], v[148:151], v[196:199], v[88:91]
	ds_read_b128 v[196:199], v174 offset:12288
	s_waitcnt lgkmcnt(3)
	v_mfma_f32_16x16x32_bf16 v[116:119], v[136:139], v[200:203], v[116:119]
	v_mfma_f32_16x16x32_bf16 v[124:127], v[140:143], v[200:203], v[124:127]
	v_mfma_f32_16x16x32_bf16 v[84:87], v[144:147], v[200:203], v[84:87]
	v_mfma_f32_16x16x32_bf16 v[92:95], v[148:151], v[200:203], v[92:95]
	ds_read_b128 v[200:203], v174 offset:13312
	s_waitcnt lgkmcnt(3)
	v_mfma_f32_16x16x32_bf16 v[96:99], v[136:139], v[204:207], v[96:99]
	v_mfma_f32_16x16x32_bf16 v[104:107], v[140:143], v[204:207], v[104:107]
	v_mfma_f32_16x16x32_bf16 v[64:67], v[144:147], v[204:207], v[64:67]
	v_mfma_f32_16x16x32_bf16 v[72:75], v[148:151], v[204:207], v[72:75]
	ds_read_b128 v[204:207], v174 offset:14336
	s_waitcnt lgkmcnt(3)
	v_mfma_f32_16x16x32_bf16 v[100:103], v[136:139], v[242:245], v[100:103]
	v_mfma_f32_16x16x32_bf16 v[108:111], v[140:143], v[242:245], v[108:111]
	v_mfma_f32_16x16x32_bf16 v[68:71], v[144:147], v[242:245], v[68:71]
	v_mfma_f32_16x16x32_bf16 v[76:79], v[148:151], v[242:245], v[76:79]
	ds_read_b128 v[242:245], v174 offset:15360
	s_waitcnt lgkmcnt(3)
	v_mfma_f32_16x16x32_bf16 v[48:51], v[136:139], v[196:199], v[48:51]
	v_mfma_f32_16x16x32_bf16 v[56:59], v[140:143], v[196:199], v[56:59]
	v_mfma_f32_16x16x32_bf16 v[16:19], v[144:147], v[196:199], v[16:19]
	v_mfma_f32_16x16x32_bf16 v[24:27], v[148:151], v[196:199], v[24:27]
	s_waitcnt lgkmcnt(2)
	v_mfma_f32_16x16x32_bf16 v[52:55], v[136:139], v[200:203], v[52:55]
	v_mfma_f32_16x16x32_bf16 v[60:63], v[140:143], v[200:203], v[60:63]
	v_mfma_f32_16x16x32_bf16 v[20:23], v[144:147], v[200:203], v[20:23]
	v_mfma_f32_16x16x32_bf16 v[28:31], v[148:151], v[200:203], v[28:31]
	s_waitcnt lgkmcnt(1)
	v_mfma_f32_16x16x32_bf16 v[32:35], v[136:139], v[204:207], v[32:35]
	v_mfma_f32_16x16x32_bf16 v[40:43], v[140:143], v[204:207], v[40:43]
	v_mfma_f32_16x16x32_bf16 v[0:3], v[144:147], v[204:207], v[0:3]
	v_mfma_f32_16x16x32_bf16 v[8:11], v[148:151], v[204:207], v[8:11]
	s_waitcnt lgkmcnt(0)
	v_mfma_f32_16x16x32_bf16 v[36:39], v[136:139], v[242:245], v[36:39]
	v_mfma_f32_16x16x32_bf16 v[44:47], v[140:143], v[242:245], v[44:47]
	v_mfma_f32_16x16x32_bf16 v[4:7], v[144:147], v[242:245], v[4:7]
	v_mfma_f32_16x16x32_bf16 v[12:15], v[148:151], v[242:245], v[12:15]
	global_load_dwordx4 v[136:139], v[248:249], off
	global_load_dwordx4 v[140:143], v[248:249], off offset:256
	global_load_dwordx4 v[144:147], v[250:251], off
	global_load_dwordx4 v[148:151], v[250:251], off offset:256
	s_waitcnt vmcnt(10)
	s_barrier
	s_add_i32 s8, s1, 7
	s_lshl_b32 s96, s8, 13
	s_add_i32 m0, vcc_lo, 8192
	v_lshl_add_u64 v[128:129], v[172:173], 0, s[96:97]
	global_load_lds_dwordx4 v[128:129], off
	global_load_lds_dwordx4 v[128:129], off offset:1024
	ds_read_b128 v[196:199], v174 offset:16384
	ds_read_b128 v[200:203], v174 offset:17408
	ds_read_b128 v[204:207], v174 offset:18432
	ds_read_b128 v[242:245], v174 offset:19456
	s_add_i32 s8, s1, 7
	s_lshl_b32 s96, s8, 11
	v_lshl_add_u64 v[248:249], v[168:169], 0, s[96:97]
	v_lshl_add_u64 v[250:251], v[170:171], 0, s[96:97]
	s_waitcnt vmcnt(8) lgkmcnt(3)
	v_mfma_f32_16x16x32_bf16 v[112:115], v[152:155], v[196:199], v[112:115]
	v_mfma_f32_16x16x32_bf16 v[120:123], v[156:159], v[196:199], v[120:123]
	v_mfma_f32_16x16x32_bf16 v[80:83], v[160:163], v[196:199], v[80:83]
	v_mfma_f32_16x16x32_bf16 v[88:91], v[164:167], v[196:199], v[88:91]
	ds_read_b128 v[196:199], v174 offset:20480
	s_waitcnt lgkmcnt(3)
	v_mfma_f32_16x16x32_bf16 v[116:119], v[152:155], v[200:203], v[116:119]
	v_mfma_f32_16x16x32_bf16 v[124:127], v[156:159], v[200:203], v[124:127]
	v_mfma_f32_16x16x32_bf16 v[84:87], v[160:163], v[200:203], v[84:87]
	v_mfma_f32_16x16x32_bf16 v[92:95], v[164:167], v[200:203], v[92:95]
	ds_read_b128 v[200:203], v174 offset:21504
	s_waitcnt lgkmcnt(3)
	v_mfma_f32_16x16x32_bf16 v[96:99], v[152:155], v[204:207], v[96:99]
	v_mfma_f32_16x16x32_bf16 v[104:107], v[156:159], v[204:207], v[104:107]
	v_mfma_f32_16x16x32_bf16 v[64:67], v[160:163], v[204:207], v[64:67]
	v_mfma_f32_16x16x32_bf16 v[72:75], v[164:167], v[204:207], v[72:75]
	ds_read_b128 v[204:207], v174 offset:22528
	s_waitcnt lgkmcnt(3)
	v_mfma_f32_16x16x32_bf16 v[100:103], v[152:155], v[242:245], v[100:103]
	v_mfma_f32_16x16x32_bf16 v[108:111], v[156:159], v[242:245], v[108:111]
	v_mfma_f32_16x16x32_bf16 v[68:71], v[160:163], v[242:245], v[68:71]
	v_mfma_f32_16x16x32_bf16 v[76:79], v[164:167], v[242:245], v[76:79]
	ds_read_b128 v[242:245], v174 offset:23552
	s_waitcnt lgkmcnt(3)
	v_mfma_f32_16x16x32_bf16 v[48:51], v[152:155], v[196:199], v[48:51]
	v_mfma_f32_16x16x32_bf16 v[56:59], v[156:159], v[196:199], v[56:59]
	v_mfma_f32_16x16x32_bf16 v[16:19], v[160:163], v[196:199], v[16:19]
	v_mfma_f32_16x16x32_bf16 v[24:27], v[164:167], v[196:199], v[24:27]
	s_waitcnt lgkmcnt(2)
	v_mfma_f32_16x16x32_bf16 v[52:55], v[152:155], v[200:203], v[52:55]
	v_mfma_f32_16x16x32_bf16 v[60:63], v[156:159], v[200:203], v[60:63]
	v_mfma_f32_16x16x32_bf16 v[20:23], v[160:163], v[200:203], v[20:23]
	v_mfma_f32_16x16x32_bf16 v[28:31], v[164:167], v[200:203], v[28:31]
	s_waitcnt lgkmcnt(1)
	v_mfma_f32_16x16x32_bf16 v[32:35], v[152:155], v[204:207], v[32:35]
	v_mfma_f32_16x16x32_bf16 v[40:43], v[156:159], v[204:207], v[40:43]
	v_mfma_f32_16x16x32_bf16 v[0:3], v[160:163], v[204:207], v[0:3]
	v_mfma_f32_16x16x32_bf16 v[8:11], v[164:167], v[204:207], v[8:11]
	s_waitcnt lgkmcnt(0)
	v_mfma_f32_16x16x32_bf16 v[36:39], v[152:155], v[242:245], v[36:39]
	v_mfma_f32_16x16x32_bf16 v[44:47], v[156:159], v[242:245], v[44:47]
	v_mfma_f32_16x16x32_bf16 v[4:7], v[160:163], v[242:245], v[4:7]
	v_mfma_f32_16x16x32_bf16 v[12:15], v[164:167], v[242:245], v[12:15]
	global_load_dwordx4 v[152:155], v[248:249], off
	global_load_dwordx4 v[156:159], v[248:249], off offset:256
	global_load_dwordx4 v[160:163], v[250:251], off
	global_load_dwordx4 v[164:167], v[250:251], off offset:256
	s_waitcnt vmcnt(10)
	s_barrier
	s_add_i32 s1, s1, 6
	s_cmp_lt_u32 s1, 30
	s_cbranch_scc1 .Lg16_gu_k
	ds_read_b128 v[196:199], v174 offset:0
	ds_read_b128 v[200:203], v174 offset:1024
	ds_read_b128 v[204:207], v174 offset:2048
	ds_read_b128 v[242:245], v174 offset:3072
	s_waitcnt vmcnt(6) lgkmcnt(3)
	v_mfma_f32_16x16x32_bf16 v[112:115], v[136:139], v[196:199], v[112:115]
	v_mfma_f32_16x16x32_bf16 v[120:123], v[140:143], v[196:199], v[120:123]
	v_mfma_f32_16x16x32_bf16 v[80:83], v[144:147], v[196:199], v[80:83]
	v_mfma_f32_16x16x32_bf16 v[88:91], v[148:151], v[196:199], v[88:91]
	ds_read_b128 v[196:199], v174 offset:4096
	s_waitcnt lgkmcnt(3)
	v_mfma_f32_16x16x32_bf16 v[116:119], v[136:139], v[200:203], v[116:119]
	v_mfma_f32_16x16x32_bf16 v[124:127], v[140:143], v[200:203], v[124:127]
	v_mfma_f32_16x16x32_bf16 v[84:87], v[144:147], v[200:203], v[84:87]
	v_mfma_f32_16x16x32_bf16 v[92:95], v[148:151], v[200:203], v[92:95]
	ds_read_b128 v[200:203], v174 offset:5120
	s_waitcnt lgkmcnt(3)
	v_mfma_f32_16x16x32_bf16 v[96:99], v[136:139], v[204:207], v[96:99]
	v_mfma_f32_16x16x32_bf16 v[104:107], v[140:143], v[204:207], v[104:107]
	v_mfma_f32_16x16x32_bf16 v[64:67], v[144:147], v[204:207], v[64:67]
	v_mfma_f32_16x16x32_bf16 v[72:75], v[148:151], v[204:207], v[72:75]
	ds_read_b128 v[204:207], v174 offset:6144
	s_waitcnt lgkmcnt(3)
	v_mfma_f32_16x16x32_bf16 v[100:103], v[136:139], v[242:245], v[100:103]
	v_mfma_f32_16x16x32_bf16 v[108:111], v[140:143], v[242:245], v[108:111]
	v_mfma_f32_16x16x32_bf16 v[68:71], v[144:147], v[242:245], v[68:71]
	v_mfma_f32_16x16x32_bf16 v[76:79], v[148:151], v[242:245], v[76:79]
	ds_read_b128 v[242:245], v174 offset:7168
	s_waitcnt lgkmcnt(3)
	v_mfma_f32_16x16x32_bf16 v[48:51], v[136:139], v[196:199], v[48:51]
	v_mfma_f32_16x16x32_bf16 v[56:59], v[140:143], v[196:199], v[56:59]
	v_mfma_f32_16x16x32_bf16 v[16:19], v[144:147], v[196:199], v[16:19]
	v_mfma_f32_16x16x32_bf16 v[24:27], v[148:151], v[196:199], v[24:27]
	s_waitcnt lgkmcnt(2)
	v_mfma_f32_16x16x32_bf16 v[52:55], v[136:139], v[200:203], v[52:55]
	v_mfma_f32_16x16x32_bf16 v[60:63], v[140:143], v[200:203], v[60:63]
	v_mfma_f32_16x16x32_bf16 v[20:23], v[144:147], v[200:203], v[20:23]
	v_mfma_f32_16x16x32_bf16 v[28:31], v[148:151], v[200:203], v[28:31]
	s_waitcnt lgkmcnt(1)
	v_mfma_f32_16x16x32_bf16 v[32:35], v[136:139], v[204:207], v[32:35]
	v_mfma_f32_16x16x32_bf16 v[40:43], v[140:143], v[204:207], v[40:43]
	v_mfma_f32_16x16x32_bf16 v[0:3], v[144:147], v[204:207], v[0:3]
	v_mfma_f32_16x16x32_bf16 v[8:11], v[148:151], v[204:207], v[8:11]
	s_waitcnt lgkmcnt(0)
	v_mfma_f32_16x16x32_bf16 v[36:39], v[136:139], v[242:245], v[36:39]
	v_mfma_f32_16x16x32_bf16 v[44:47], v[140:143], v[242:245], v[44:47]
	v_mfma_f32_16x16x32_bf16 v[4:7], v[144:147], v[242:245], v[4:7]
	v_mfma_f32_16x16x32_bf16 v[12:15], v[148:151], v[242:245], v[12:15]
	s_waitcnt vmcnt(4)
	s_barrier
	ds_read_b128 v[196:199], v174 offset:8192
	ds_read_b128 v[200:203], v174 offset:9216
	ds_read_b128 v[204:207], v174 offset:10240
	ds_read_b128 v[242:245], v174 offset:11264
	s_waitcnt vmcnt(0) lgkmcnt(3)
	v_mfma_f32_16x16x32_bf16 v[112:115], v[152:155], v[196:199], v[112:115]
	v_mfma_f32_16x16x32_bf16 v[120:123], v[156:159], v[196:199], v[120:123]
	v_mfma_f32_16x16x32_bf16 v[80:83], v[160:163], v[196:199], v[80:83]
	v_mfma_f32_16x16x32_bf16 v[88:91], v[164:167], v[196:199], v[88:91]
	ds_read_b128 v[196:199], v174 offset:12288
	s_waitcnt lgkmcnt(3)
	v_mfma_f32_16x16x32_bf16 v[116:119], v[152:155], v[200:203], v[116:119]
	v_mfma_f32_16x16x32_bf16 v[124:127], v[156:159], v[200:203], v[124:127]
	v_mfma_f32_16x16x32_bf16 v[84:87], v[160:163], v[200:203], v[84:87]
	v_mfma_f32_16x16x32_bf16 v[92:95], v[164:167], v[200:203], v[92:95]
	ds_read_b128 v[200:203], v174 offset:13312
	s_waitcnt lgkmcnt(3)
	v_mfma_f32_16x16x32_bf16 v[96:99], v[152:155], v[204:207], v[96:99]
	v_mfma_f32_16x16x32_bf16 v[104:107], v[156:159], v[204:207], v[104:107]
	v_mfma_f32_16x16x32_bf16 v[64:67], v[160:163], v[204:207], v[64:67]
	v_mfma_f32_16x16x32_bf16 v[72:75], v[164:167], v[204:207], v[72:75]
	ds_read_b128 v[204:207], v174 offset:14336
	s_waitcnt lgkmcnt(3)
	v_mfma_f32_16x16x32_bf16 v[100:103], v[152:155], v[242:245], v[100:103]
	v_mfma_f32_16x16x32_bf16 v[108:111], v[156:159], v[242:245], v[108:111]
	v_mfma_f32_16x16x32_bf16 v[68:71], v[160:163], v[242:245], v[68:71]
	v_mfma_f32_16x16x32_bf16 v[76:79], v[164:167], v[242:245], v[76:79]
	ds_read_b128 v[242:245], v174 offset:15360
	v_permlane16_swap_b32_e32 v112, v116
	v_permlane16_swap_b32_e32 v113, v117
	v_permlane16_swap_b32_e32 v114, v118
	v_permlane16_swap_b32_e32 v115, v119
	v_permlane16_swap_b32_e32 v120, v124
	v_permlane16_swap_b32_e32 v121, v125
	v_permlane16_swap_b32_e32 v122, v126
	v_permlane16_swap_b32_e32 v123, v127
	v_permlane16_swap_b32_e32 v80, v84
	v_permlane16_swap_b32_e32 v81, v85
	v_permlane16_swap_b32_e32 v82, v86
	v_permlane16_swap_b32_e32 v83, v87
	v_permlane16_swap_b32_e32 v88, v92
	v_permlane16_swap_b32_e32 v89, v93
	v_permlane16_swap_b32_e32 v90, v94
	v_permlane16_swap_b32_e32 v91, v95
	v_permlane32_swap_b32_e32 v112, v116
	v_permlane32_swap_b32_e32 v113, v117
	v_permlane32_swap_b32_e32 v114, v118
	v_permlane32_swap_b32_e32 v115, v119
	v_permlane32_swap_b32_e32 v120, v124
	v_permlane32_swap_b32_e32 v121, v125
	v_permlane32_swap_b32_e32 v122, v126
	v_permlane32_swap_b32_e32 v123, v127
	v_permlane32_swap_b32_e32 v80, v84
	v_permlane32_swap_b32_e32 v81, v85
	v_permlane32_swap_b32_e32 v82, v86
	v_permlane32_swap_b32_e32 v83, v87
	v_permlane32_swap_b32_e32 v88, v92
	v_permlane32_swap_b32_e32 v89, v93
	v_permlane32_swap_b32_e32 v90, v94
	v_permlane32_swap_b32_e32 v91, v95
	s_waitcnt lgkmcnt(3)
	v_mfma_f32_16x16x32_bf16 v[48:51], v[152:155], v[196:199], v[48:51]
	v_mfma_f32_16x16x32_bf16 v[56:59], v[156:159], v[196:199], v[56:59]
	v_mfma_f32_16x16x32_bf16 v[16:19], v[160:163], v[196:199], v[16:19]
	v_mfma_f32_16x16x32_bf16 v[24:27], v[164:167], v[196:199], v[24:27]
	s_waitcnt lgkmcnt(2)
	v_mfma_f32_16x16x32_bf16 v[52:55], v[152:155], v[200:203], v[52:55]
	v_mfma_f32_16x16x32_bf16 v[60:63], v[156:159], v[200:203], v[60:63]
	v_mfma_f32_16x16x32_bf16 v[20:23], v[160:163], v[200:203], v[20:23]
	v_mfma_f32_16x16x32_bf16 v[28:31], v[164:167], v[200:203], v[28:31]
	v_permlane16_swap_b32_e32 v96, v100
	v_permlane16_swap_b32_e32 v97, v101
	v_permlane16_swap_b32_e32 v98, v102
	v_permlane16_swap_b32_e32 v99, v103
	v_permlane16_swap_b32_e32 v104, v108
	v_permlane16_swap_b32_e32 v105, v109
	v_permlane16_swap_b32_e32 v106, v110
	v_permlane16_swap_b32_e32 v107, v111
	v_permlane16_swap_b32_e32 v64, v68
	v_permlane16_swap_b32_e32 v65, v69
	v_permlane16_swap_b32_e32 v66, v70
	v_permlane16_swap_b32_e32 v67, v71
	v_permlane16_swap_b32_e32 v72, v76
	v_permlane16_swap_b32_e32 v73, v77
	v_permlane16_swap_b32_e32 v74, v78
	v_permlane16_swap_b32_e32 v75, v79
	v_permlane32_swap_b32_e32 v96, v100
	v_permlane32_swap_b32_e32 v97, v101
	v_permlane32_swap_b32_e32 v98, v102
	v_permlane32_swap_b32_e32 v99, v103
	v_permlane32_swap_b32_e32 v104, v108
	v_permlane32_swap_b32_e32 v105, v109
	v_permlane32_swap_b32_e32 v106, v110
	v_permlane32_swap_b32_e32 v107, v111
	v_permlane32_swap_b32_e32 v64, v68
	v_permlane32_swap_b32_e32 v65, v69
	v_permlane32_swap_b32_e32 v66, v70
	v_permlane32_swap_b32_e32 v67, v71
	v_permlane32_swap_b32_e32 v72, v76
	v_permlane32_swap_b32_e32 v73, v77
	v_permlane32_swap_b32_e32 v74, v78
	v_permlane32_swap_b32_e32 v75, v79
	s_waitcnt lgkmcnt(1)
	v_mfma_f32_16x16x32_bf16 v[32:35], v[152:155], v[204:207], v[32:35]
	v_mfma_f32_16x16x32_bf16 v[40:43], v[156:159], v[204:207], v[40:43]
	v_mfma_f32_16x16x32_bf16 v[0:3], v[160:163], v[204:207], v[0:3]
	v_mfma_f32_16x16x32_bf16 v[8:11], v[164:167], v[204:207], v[8:11]
	s_waitcnt lgkmcnt(0)
	v_mfma_f32_16x16x32_bf16 v[36:39], v[152:155], v[242:245], v[36:39]
	v_mfma_f32_16x16x32_bf16 v[44:47], v[156:159], v[242:245], v[44:47]
	v_mfma_f32_16x16x32_bf16 v[4:7], v[160:163], v[242:245], v[4:7]
	v_mfma_f32_16x16x32_bf16 v[12:15], v[164:167], v[242:245], v[12:15]
	v_permlane16_swap_b32_e32 v48, v52
	v_permlane16_swap_b32_e32 v49, v53
	v_permlane16_swap_b32_e32 v50, v54
	v_permlane16_swap_b32_e32 v51, v55
	v_permlane16_swap_b32_e32 v56, v60
	v_permlane16_swap_b32_e32 v57, v61
	v_permlane16_swap_b32_e32 v58, v62
	v_permlane16_swap_b32_e32 v59, v63
	v_permlane16_swap_b32_e32 v16, v20
	v_permlane16_swap_b32_e32 v17, v21
	v_permlane16_swap_b32_e32 v18, v22
	v_permlane16_swap_b32_e32 v19, v23
	v_permlane16_swap_b32_e32 v24, v28
	v_permlane16_swap_b32_e32 v25, v29
	v_permlane16_swap_b32_e32 v26, v30
	v_permlane16_swap_b32_e32 v27, v31
	v_permlane32_swap_b32_e32 v48, v52
	v_permlane32_swap_b32_e32 v49, v53
	v_permlane32_swap_b32_e32 v50, v54
	v_permlane32_swap_b32_e32 v51, v55
	v_permlane32_swap_b32_e32 v56, v60
	v_permlane32_swap_b32_e32 v57, v61
	v_permlane32_swap_b32_e32 v58, v62
	v_permlane32_swap_b32_e32 v59, v63
	v_permlane32_swap_b32_e32 v16, v20
	v_permlane32_swap_b32_e32 v17, v21
	v_permlane32_swap_b32_e32 v18, v22
	v_permlane32_swap_b32_e32 v19, v23
	v_permlane32_swap_b32_e32 v24, v28
	v_permlane32_swap_b32_e32 v25, v29
	v_permlane32_swap_b32_e32 v26, v30
	v_permlane32_swap_b32_e32 v27, v31
	s_barrier
	v_readlane_b32 s8, v254, 11
	s_mov_b32 s100, 0
	s_add_i32 s8, s2, s8
	s_cmp_ge_i32 s8, s3
	s_cbranch_scc1 .Lg16_gu_np
	s_mul_hi_i32 s9, s8, 0x2e8ba2e9
	s_ashr_i32 s9, s9, 6
	s_lshl_b32 s1, s9, 3
	s_sub_i32 s96, s25, s1
	s_mulk_i32 s9, 0x160
	s_sub_i32 s8, s8, s9
	s_cmp_ge_i32 s96, 8
	s_cbranch_scc1 .Lg16_gu_gs8
	s_cmp_eq_u32 s96, 1
	s_cbranch_scc0 .Lg16_gu_np
	s_mov_b32 s9, 0
	s_branch .Lg16_gu_have
.Lg16_gu_gs8:
	s_and_b32 s9, s8, 7
	s_lshr_b32 s8, s8, 3
.Lg16_gu_have:
	s_add_i32 s9, s9, s1
	s_add_i32 s9, s9, s6
	s_sub_i32 s9, s9, s7
	s_lshl_b32 s9, s9, 19
	s_sub_i32 s8, s8, s0
	s_lshl_b32 s1, s8, 18
	s_mov_b32 s8, s9
	s_ashr_i32 s9, s9, 31
	v_lshl_add_u64 v[168:169], v[168:169], 0, s[8:9]
	v_lshl_add_u64 v[170:171], v[170:171], 0, s[8:9]
	s_mov_b32 s8, s1
	s_ashr_i32 s9, s1, 31
	v_lshl_add_u64 v[172:173], v[172:173], 0, s[8:9]
	s_mov_b32 s96, 0
	s_mov_b32 m0, vcc_lo
	v_lshl_add_u64 v[128:129], v[172:173], 0, s[96:97]
	global_load_lds_dwordx4 v[128:129], off
	global_load_lds_dwordx4 v[128:129], off offset:1024
	s_mov_b32 s96, 0
	v_lshl_add_u64 v[248:249], v[168:169], 0, s[96:97]
	v_lshl_add_u64 v[250:251], v[170:171], 0, s[96:97]
	global_load_dwordx4 v[136:139], v[248:249], off
	global_load_dwordx4 v[140:143], v[248:249], off offset:256
	global_load_dwordx4 v[144:147], v[250:251], off
	global_load_dwordx4 v[148:151], v[250:251], off offset:256
	s_movk_i32 s96, 0x2000
	s_add_i32 m0, vcc_lo, 8192
	v_lshl_add_u64 v[128:129], v[172:173], 0, s[96:97]
	global_load_lds_dwordx4 v[128:129], off
	global_load_lds_dwordx4 v[128:129], off offset:1024
	s_movk_i32 s96, 0x800
	v_lshl_add_u64 v[248:249], v[168:169], 0, s[96:97]
	v_lshl_add_u64 v[250:251], v[170:171], 0, s[96:97]
	global_load_dwordx4 v[152:155], v[248:249], off
	global_load_dwordx4 v[156:159], v[248:249], off offset:256
	global_load_dwordx4 v[160:163], v[250:251], off
	global_load_dwordx4 v[164:167], v[250:251], off offset:256
	s_mov_b32 s100, 1
.Lg16_gu_np:
	s_nop 7
	v_permlane16_swap_b32_e32 v32, v36
	v_permlane16_swap_b32_e32 v33, v37
	v_permlane16_swap_b32_e32 v34, v38
	v_permlane16_swap_b32_e32 v35, v39
	v_permlane16_swap_b32_e32 v40, v44
	v_permlane16_swap_b32_e32 v41, v45
	v_permlane16_swap_b32_e32 v42, v46
	v_permlane16_swap_b32_e32 v43, v47
	v_permlane16_swap_b32_e32 v0, v4
	v_permlane16_swap_b32_e32 v1, v5
	v_permlane16_swap_b32_e32 v2, v6
	v_permlane16_swap_b32_e32 v3, v7
	v_permlane16_swap_b32_e32 v8, v12
	v_permlane16_swap_b32_e32 v9, v13
	v_permlane16_swap_b32_e32 v10, v14
	v_permlane16_swap_b32_e32 v11, v15
	v_permlane32_swap_b32_e32 v32, v36
	v_permlane32_swap_b32_e32 v33, v37
	v_permlane32_swap_b32_e32 v34, v38
	v_permlane32_swap_b32_e32 v35, v39
	v_permlane32_swap_b32_e32 v40, v44
	v_permlane32_swap_b32_e32 v41, v45
	v_permlane32_swap_b32_e32 v42, v46
	v_permlane32_swap_b32_e32 v43, v47
	v_permlane32_swap_b32_e32 v0, v4
	v_permlane32_swap_b32_e32 v1, v5
	v_permlane32_swap_b32_e32 v2, v6
	v_permlane32_swap_b32_e32 v3, v7
	v_permlane32_swap_b32_e32 v8, v12
	v_permlane32_swap_b32_e32 v9, v13
	v_permlane32_swap_b32_e32 v10, v14
	v_permlane32_swap_b32_e32 v11, v15
	v_mul_f32_e32 v133, 0xbfb8aa3b, v112
	v_exp_f32_e32 v133, v133
	s_movk_i32 s1, 0x2400
	v_mul_lo_u32 v128, v238, s1
	v_lshl_or_b32 v131, s0, 6, v181
	v_add_f32_e32 v133, 1.0, v133
	v_lshl_or_b32 v132, v239, 1, v128
	v_and_b32_e32 v129, 0xffffffc0, v237
	v_lshl_or_b32 v128, v181, 1, v128
	v_rcp_f32_e32 v135, v133
	s_nop 0
	v_mul_f32_e32 v112, v112, v135
	v_mul_f32_e32 v96, v96, v112
	v_cvt_pk_bf16_f32 v112, v96, s0
	s_movk_i32 s0, 0x240
	v_mad_u32_u24 v96, v183, s0, v132
	ds_write_b16 v96, v112
	v_mul_f32_e32 v112, 0xbfb8aa3b, v113
	v_exp_f32_e32 v112, v112
	v_lshl_add_u32 v130, s7, 8, v129
	v_lshrrev_b32_e32 v129, 2, v240
	v_mad_u32_u24 v128, v129, s42, v128
	v_add_f32_e32 v112, 1.0, v112
	v_rcp_f32_e32 v133, v112
	s_nop 0
	v_mul_f32_e32 v112, v113, v133
	v_mul_f32_e32 v97, v97, v112
	v_cvt_pk_bf16_f32 v97, v97, s0
	ds_write_b16 v96, v97 offset:144
	v_mul_f32_e32 v97, 0xbfb8aa3b, v114
	v_exp_f32_e32 v97, v97
	s_nop 0
	v_add_f32_e32 v97, 1.0, v97
	v_rcp_f32_e32 v113, v97
	s_nop 0
	v_mul_f32_e32 v97, v114, v113
	v_mul_f32_e32 v97, v98, v97
	v_cvt_pk_bf16_f32 v97, v97, s0
	ds_write_b16 v96, v97 offset:288
	v_mul_f32_e32 v97, 0xbfb8aa3b, v115
	v_exp_f32_e32 v97, v97
	s_nop 0
	v_add_f32_e32 v97, 1.0, v97
	v_rcp_f32_e32 v112, v97
	s_nop 0
	v_mul_f32_e32 v97, v115, v112
	v_mul_f32_e32 v97, v99, v97
	v_cvt_pk_bf16_f32 v97, v97, s0
	ds_write_b16 v96, v97 offset:432
	v_mul_f32_e32 v97, 0xbfb8aa3b, v116
	v_exp_f32_e32 v97, v97
	s_nop 0
	v_add_f32_e32 v97, 1.0, v97
	v_rcp_f32_e32 v99, v97
	s_nop 0
	v_mul_f32_e32 v97, v116, v99
	v_mul_f32_e32 v97, v100, v97
	v_cvt_pk_bf16_f32 v97, v97, s0
	ds_write_b16 v96, v97 offset:1152
	v_mul_f32_e32 v97, 0xbfb8aa3b, v117
	v_exp_f32_e32 v97, v97
	s_nop 0
	v_add_f32_e32 v97, 1.0, v97
	v_rcp_f32_e32 v99, v97
	s_nop 0
	v_mul_f32_e32 v97, v117, v99
	v_mul_f32_e32 v97, v101, v97
	v_cvt_pk_bf16_f32 v97, v97, s0
	ds_write_b16 v96, v97 offset:1296
	v_mul_f32_e32 v97, 0xbfb8aa3b, v118
	v_exp_f32_e32 v97, v97
	s_nop 0
	v_add_f32_e32 v97, 1.0, v97
	v_rcp_f32_e32 v99, v97
	s_nop 0
	v_mul_f32_e32 v97, v118, v99
	v_mul_f32_e32 v97, v102, v97
	v_cvt_pk_bf16_f32 v97, v97, s0
	ds_write_b16 v96, v97 offset:1440
	v_mul_f32_e32 v97, 0xbfb8aa3b, v119
	v_exp_f32_e32 v97, v97
	s_nop 0
	v_add_f32_e32 v97, 1.0, v97
	v_rcp_f32_e32 v99, v97
	s_nop 0
	v_mul_f32_e32 v97, v119, v99
	v_mul_f32_e32 v97, v103, v97
	v_cvt_pk_bf16_f32 v97, v97, s0
	ds_write_b16 v96, v97 offset:1584
	v_mul_f32_e32 v97, 0xbfb8aa3b, v120
	v_exp_f32_e32 v97, v97
	s_nop 0
	v_add_f32_e32 v97, 1.0, v97
	v_rcp_f32_e32 v99, v97
	s_nop 0
	v_mul_f32_e32 v97, v120, v99
	v_mul_f32_e32 v97, v104, v97
	v_cvt_pk_bf16_f32 v97, v97, s0
	ds_write_b16 v96, v97 offset:2304
	v_mul_f32_e32 v97, 0xbfb8aa3b, v121
	v_exp_f32_e32 v97, v97
	s_nop 0
	v_add_f32_e32 v97, 1.0, v97
	v_rcp_f32_e32 v99, v97
	s_nop 0
	v_mul_f32_e32 v97, v121, v99
	v_mul_f32_e32 v97, v105, v97
	v_cvt_pk_bf16_f32 v97, v97, s0
	ds_write_b16 v96, v97 offset:2448
	v_mul_f32_e32 v97, 0xbfb8aa3b, v122
	v_exp_f32_e32 v97, v97
	s_nop 0
	v_add_f32_e32 v97, 1.0, v97
	v_rcp_f32_e32 v99, v97
	s_nop 0
	v_mul_f32_e32 v97, v122, v99
	v_mul_f32_e32 v97, v106, v97
	v_cvt_pk_bf16_f32 v97, v97, s0
	ds_write_b16 v96, v97 offset:2592
	v_mul_f32_e32 v97, 0xbfb8aa3b, v123
	v_exp_f32_e32 v97, v97
	s_nop 0
	v_add_f32_e32 v97, 1.0, v97
	v_rcp_f32_e32 v99, v97
	s_nop 0
	v_mul_f32_e32 v97, v123, v99
	v_mul_f32_e32 v97, v107, v97
	v_cvt_pk_bf16_f32 v97, v97, s0
	ds_write_b16 v96, v97 offset:2736
	v_mul_f32_e32 v97, 0xbfb8aa3b, v124
	v_exp_f32_e32 v97, v97
	s_nop 0
	v_add_f32_e32 v97, 1.0, v97
	v_rcp_f32_e32 v99, v97
	s_nop 0
	v_mul_f32_e32 v97, v124, v99
	v_mul_f32_e32 v97, v108, v97
	v_cvt_pk_bf16_f32 v97, v97, s0
	ds_write_b16 v96, v97 offset:3456
	v_mul_f32_e32 v97, 0xbfb8aa3b, v125
	v_exp_f32_e32 v97, v97
	s_nop 0
	v_add_f32_e32 v97, 1.0, v97
	v_rcp_f32_e32 v99, v97
	s_nop 0
	v_mul_f32_e32 v97, v125, v99
	v_mul_f32_e32 v97, v109, v97
	v_cvt_pk_bf16_f32 v97, v97, s0
	ds_write_b16 v96, v97 offset:3600
	v_mul_f32_e32 v97, 0xbfb8aa3b, v126
	v_exp_f32_e32 v97, v97
	s_nop 0
	v_add_f32_e32 v97, 1.0, v97
	v_rcp_f32_e32 v99, v97
	s_nop 0
	v_mul_f32_e32 v97, v126, v99
	v_mul_f32_e32 v97, v110, v97
	v_cvt_pk_bf16_f32 v97, v97, s0
	ds_write_b16 v96, v97 offset:3744
	v_mul_f32_e32 v97, 0xbfb8aa3b, v127
	v_exp_f32_e32 v97, v97
	s_nop 0
	v_add_f32_e32 v97, 1.0, v97
	v_rcp_f32_e32 v99, v97
	s_nop 0
	v_mul_f32_e32 v97, v127, v99
	v_mul_f32_e32 v97, v111, v97
	v_cvt_pk_bf16_f32 v97, v97, s0
	ds_write_b16 v96, v97 offset:3888
	v_mul_f32_e32 v97, 0xbfb8aa3b, v80
	v_exp_f32_e32 v97, v97
	s_nop 0
	v_add_f32_e32 v97, 1.0, v97
	v_rcp_f32_e32 v99, v97
	s_nop 0
	v_mul_f32_e32 v80, v80, v99
	v_mul_f32_e32 v64, v64, v80
	v_cvt_pk_bf16_f32 v64, v64, s0
	ds_write_b16 v96, v64 offset:4608
	v_mul_f32_e32 v64, 0xbfb8aa3b, v81
	v_exp_f32_e32 v64, v64
	s_nop 0
	v_add_f32_e32 v64, 1.0, v64
	v_rcp_f32_e32 v97, v64
	s_nop 0
	v_mul_f32_e32 v64, v81, v97
	v_mul_f32_e32 v64, v65, v64
	v_cvt_pk_bf16_f32 v64, v64, s0
	ds_write_b16 v96, v64 offset:4752
	v_mul_f32_e32 v64, 0xbfb8aa3b, v82
	v_exp_f32_e32 v64, v64
	s_nop 0
	v_add_f32_e32 v64, 1.0, v64
	v_rcp_f32_e32 v80, v64
	s_nop 0
	v_mul_f32_e32 v64, v82, v80
	v_mul_f32_e32 v64, v66, v64
	v_cvt_pk_bf16_f32 v64, v64, s0
	ds_write_b16 v96, v64 offset:4896
	v_mul_f32_e32 v64, 0xbfb8aa3b, v83
	v_exp_f32_e32 v64, v64
	s_nop 0
	v_add_f32_e32 v64, 1.0, v64
	v_rcp_f32_e32 v66, v64
	s_nop 0
	v_mul_f32_e32 v64, v83, v66
	v_mul_f32_e32 v64, v67, v64
	v_cvt_pk_bf16_f32 v64, v64, s0
	ds_write_b16 v96, v64 offset:5040
	v_mul_f32_e32 v64, 0xbfb8aa3b, v84
	v_exp_f32_e32 v64, v64
	s_nop 0
	v_add_f32_e32 v64, 1.0, v64
	v_rcp_f32_e32 v66, v64
	s_nop 0
	v_mul_f32_e32 v64, v84, v66
	v_mul_f32_e32 v64, v68, v64
	v_cvt_pk_bf16_f32 v64, v64, s0
	ds_write_b16 v96, v64 offset:5760
	v_mul_f32_e32 v64, 0xbfb8aa3b, v85
	v_exp_f32_e32 v64, v64
	s_nop 0
	v_add_f32_e32 v64, 1.0, v64
	v_rcp_f32_e32 v66, v64
	s_nop 0
	v_mul_f32_e32 v64, v85, v66
	v_mul_f32_e32 v64, v69, v64
	v_cvt_pk_bf16_f32 v64, v64, s0
	ds_write_b16 v96, v64 offset:5904
	v_mul_f32_e32 v64, 0xbfb8aa3b, v86
	v_exp_f32_e32 v64, v64
	s_nop 0
	v_add_f32_e32 v64, 1.0, v64
	v_rcp_f32_e32 v66, v64
	s_nop 0
	v_mul_f32_e32 v64, v86, v66
	v_mul_f32_e32 v64, v70, v64
	v_cvt_pk_bf16_f32 v64, v64, s0
	ds_write_b16 v96, v64 offset:6048
	v_mul_f32_e32 v64, 0xbfb8aa3b, v87
	v_exp_f32_e32 v64, v64
	s_nop 0
	v_add_f32_e32 v64, 1.0, v64
	v_rcp_f32_e32 v66, v64
	s_nop 0
	v_mul_f32_e32 v64, v87, v66
	v_mul_f32_e32 v64, v71, v64
	v_cvt_pk_bf16_f32 v64, v64, s0
	ds_write_b16 v96, v64 offset:6192
	v_mul_f32_e32 v64, 0xbfb8aa3b, v88
	v_exp_f32_e32 v64, v64
	v_ashrrev_i32_e32 v71, 5, v130
	v_or_b32_e32 v70, 1, v71
	v_add_f32_e32 v64, 1.0, v64
	v_rcp_f32_e32 v66, v64
	s_nop 0
	v_mul_f32_e32 v64, v88, v66
	v_mul_f32_e32 v64, v72, v64
	v_cvt_pk_bf16_f32 v64, v64, s0
	ds_write_b16 v96, v64 offset:6912
	v_mul_f32_e32 v64, 0xbfb8aa3b, v89
	v_exp_f32_e32 v64, v64
	s_nop 0
	v_add_f32_e32 v64, 1.0, v64
	v_rcp_f32_e32 v66, v64
	s_nop 0
	v_mul_f32_e32 v64, v89, v66
	v_mul_f32_e32 v64, v73, v64
	v_cvt_pk_bf16_f32 v64, v64, s0
	ds_write_b16 v96, v64 offset:7056
	v_mul_f32_e32 v64, 0xbfb8aa3b, v90
	v_exp_f32_e32 v64, v64
	s_nop 0
	v_add_f32_e32 v64, 1.0, v64
	v_rcp_f32_e32 v66, v64
	s_nop 0
	v_mul_f32_e32 v64, v90, v66
	v_mul_f32_e32 v64, v74, v64
	v_cvt_pk_bf16_f32 v64, v64, s0
	ds_write_b16 v96, v64 offset:7200
	v_mul_f32_e32 v64, 0xbfb8aa3b, v91
	v_exp_f32_e32 v64, v64
	s_nop 0
	v_add_f32_e32 v64, 1.0, v64
	v_rcp_f32_e32 v66, v64
	s_nop 0
	v_mul_f32_e32 v64, v91, v66
	v_mul_f32_e32 v64, v75, v64
	v_cvt_pk_bf16_f32 v64, v64, s0
	ds_write_b16 v96, v64 offset:7344
	v_mul_f32_e32 v64, 0xbfb8aa3b, v92
	v_exp_f32_e32 v64, v64
	s_nop 0
	v_add_f32_e32 v64, 1.0, v64
	v_rcp_f32_e32 v66, v64
	s_nop 0
	v_mul_f32_e32 v64, v92, v66
	v_mul_f32_e32 v64, v76, v64
	v_cvt_pk_bf16_f32 v64, v64, s0
	ds_write_b16 v96, v64 offset:8064
	v_mul_f32_e32 v64, 0xbfb8aa3b, v93
	v_exp_f32_e32 v64, v64
	s_nop 0
	v_add_f32_e32 v64, 1.0, v64
	v_rcp_f32_e32 v66, v64
	s_nop 0
	v_mul_f32_e32 v64, v93, v66
	v_mul_f32_e32 v64, v77, v64
	v_cvt_pk_bf16_f32 v64, v64, s0
	ds_write_b16 v96, v64 offset:8208
	v_mul_f32_e32 v64, 0xbfb8aa3b, v94
	v_exp_f32_e32 v64, v64
	s_nop 0
	v_add_f32_e32 v64, 1.0, v64
	v_rcp_f32_e32 v66, v64
	s_nop 0
	v_mul_f32_e32 v64, v94, v66
	v_mul_f32_e32 v64, v78, v64
	v_cvt_pk_bf16_f32 v64, v64, s0
	ds_write_b16 v96, v64 offset:8352
	v_mul_f32_e32 v64, 0xbfb8aa3b, v95
	v_exp_f32_e32 v64, v64
	s_nop 0
	v_add_f32_e32 v64, 1.0, v64
	v_rcp_f32_e32 v66, v64
	s_nop 0
	v_mul_f32_e32 v64, v95, v66
	v_mul_f32_e32 v64, v79, v64
	v_cvt_pk_bf16_f32 v64, v64, s0
	ds_write_b16 v96, v64 offset:8496
	v_ashrrev_i32_e32 v68, 4, v131
	s_waitcnt lgkmcnt(0)
	v_ashrrev_i32_e32 v69, 31, v68
	ds_read_b128 v[72:75], v128
	v_mad_i64_i32 v[64:65], s[0:1], v71, s23, v[68:69]
	v_lshlrev_b64 v[64:65], 10, v[64:65]
	v_lshlrev_b32_e32 v66, 6, v181
	v_lshl_add_u64 v[64:65], s[66:67], 0, v[64:65]
	v_and_b32_e32 v176, 0x200, v66
	v_lshl_add_u64 v[76:77], v[64:65], 0, v[176:177]
	v_lshlrev_b32_e32 v66, 4, v129
	v_mov_b32_e32 v67, v177
	v_lshl_add_u64 v[64:65], v[76:77], 0, v[66:67]
	s_waitcnt lgkmcnt(0)
	global_store_dwordx4 v[64:65], v[72:75], off
	ds_read_b128 v[72:75], v128 offset:2304
	v_or_b32_e32 v64, 0x100, v66
	v_mov_b32_e32 v65, v177
	v_lshl_add_u64 v[76:77], v[76:77], 0, v[64:65]
	s_waitcnt lgkmcnt(0)
	global_store_dwordx4 v[76:77], v[72:75], off
	ds_read_b128 v[72:75], v128 offset:4608
	v_mad_i64_i32 v[76:77], s[0:1], v70, s23, v[68:69]
	v_lshlrev_b64 v[76:77], 10, v[76:77]
	v_lshl_add_u64 v[76:77], s[66:67], 0, v[76:77]
	v_lshl_add_u64 v[76:77], v[76:77], 0, v[176:177]
	v_lshl_add_u64 v[78:79], v[76:77], 0, v[66:67]
	v_mul_f32_e32 v69, 0xbfb8aa3b, v48
	s_waitcnt lgkmcnt(0)
	global_store_dwordx4 v[78:79], v[72:75], off
	ds_read_b128 v[72:75], v128 offset:6912
	v_exp_f32_e32 v69, v69
	v_lshl_add_u64 v[76:77], v[76:77], 0, v[64:65]
	v_add_f32_e32 v69, 1.0, v69
	s_waitcnt lgkmcnt(0)
	global_store_dwordx4 v[76:77], v[72:75], off
	s_waitcnt lgkmcnt(0)
	s_nop 1
	v_rcp_f32_e32 v73, v69
	s_nop 0
	v_mul_f32_e32 v48, v48, v73
	v_mul_f32_e32 v32, v32, v48
	v_cvt_pk_bf16_f32 v32, v32, s0
	ds_write_b16 v96, v32
	v_mul_f32_e32 v32, 0xbfb8aa3b, v49
	v_exp_f32_e32 v32, v32
	s_nop 0
	v_add_f32_e32 v32, 1.0, v32
	v_rcp_f32_e32 v69, v32
	s_nop 0
	v_mul_f32_e32 v32, v49, v69
	v_mul_f32_e32 v32, v33, v32
	v_cvt_pk_bf16_f32 v32, v32, s0
	ds_write_b16 v96, v32 offset:144
	v_mul_f32_e32 v32, 0xbfb8aa3b, v50
	v_exp_f32_e32 v32, v32
	s_nop 0
	v_add_f32_e32 v32, 1.0, v32
	v_rcp_f32_e32 v48, v32
	s_nop 0
	v_mul_f32_e32 v32, v50, v48
	v_mul_f32_e32 v32, v34, v32
	v_cvt_pk_bf16_f32 v32, v32, s0
	ds_write_b16 v96, v32 offset:288
	v_mul_f32_e32 v32, 0xbfb8aa3b, v51
	v_exp_f32_e32 v32, v32
	s_nop 0
	v_add_f32_e32 v32, 1.0, v32
	v_rcp_f32_e32 v34, v32
	s_nop 0
	v_mul_f32_e32 v32, v51, v34
	v_mul_f32_e32 v32, v35, v32
	v_cvt_pk_bf16_f32 v32, v32, s0
	ds_write_b16 v96, v32 offset:432
	v_mul_f32_e32 v32, 0xbfb8aa3b, v52
	v_exp_f32_e32 v32, v32
	s_nop 0
	v_add_f32_e32 v32, 1.0, v32
	v_rcp_f32_e32 v34, v32
	s_nop 0
	v_mul_f32_e32 v32, v52, v34
	v_mul_f32_e32 v32, v36, v32
	v_cvt_pk_bf16_f32 v32, v32, s0
	ds_write_b16 v96, v32 offset:1152
	v_mul_f32_e32 v32, 0xbfb8aa3b, v53
	v_exp_f32_e32 v32, v32
	s_nop 0
	v_add_f32_e32 v32, 1.0, v32
	v_rcp_f32_e32 v34, v32
	s_nop 0
	v_mul_f32_e32 v32, v53, v34
	v_mul_f32_e32 v32, v37, v32
	v_cvt_pk_bf16_f32 v32, v32, s0
	ds_write_b16 v96, v32 offset:1296
	v_mul_f32_e32 v32, 0xbfb8aa3b, v54
	v_exp_f32_e32 v32, v32
	s_nop 0
	v_add_f32_e32 v32, 1.0, v32
	v_rcp_f32_e32 v34, v32
	s_nop 0
	v_mul_f32_e32 v32, v54, v34
	v_mul_f32_e32 v32, v38, v32
	v_cvt_pk_bf16_f32 v32, v32, s0
	ds_write_b16 v96, v32 offset:1440
	v_mul_f32_e32 v32, 0xbfb8aa3b, v55
	v_exp_f32_e32 v32, v32
	s_nop 0
	v_add_f32_e32 v32, 1.0, v32
	v_rcp_f32_e32 v34, v32
	s_nop 0
	v_mul_f32_e32 v32, v55, v34
	v_mul_f32_e32 v32, v39, v32
	v_cvt_pk_bf16_f32 v32, v32, s0
	ds_write_b16 v96, v32 offset:1584
	v_mul_f32_e32 v32, 0xbfb8aa3b, v56
	v_exp_f32_e32 v32, v32
	s_nop 0
	v_add_f32_e32 v32, 1.0, v32
	v_rcp_f32_e32 v34, v32
	s_nop 0
	v_mul_f32_e32 v32, v56, v34
	v_mul_f32_e32 v32, v40, v32
	v_cvt_pk_bf16_f32 v32, v32, s0
	ds_write_b16 v96, v32 offset:2304
	v_mul_f32_e32 v32, 0xbfb8aa3b, v57
	v_exp_f32_e32 v32, v32
	s_nop 0
	v_add_f32_e32 v32, 1.0, v32
	v_rcp_f32_e32 v34, v32
	s_nop 0
	v_mul_f32_e32 v32, v57, v34
	v_mul_f32_e32 v32, v41, v32
	v_cvt_pk_bf16_f32 v32, v32, s0
	ds_write_b16 v96, v32 offset:2448
	v_mul_f32_e32 v32, 0xbfb8aa3b, v58
	v_exp_f32_e32 v32, v32
	s_nop 0
	v_add_f32_e32 v32, 1.0, v32
	v_rcp_f32_e32 v34, v32
	s_nop 0
	v_mul_f32_e32 v32, v58, v34
	v_mul_f32_e32 v32, v42, v32
	v_cvt_pk_bf16_f32 v32, v32, s0
	ds_write_b16 v96, v32 offset:2592
	v_mul_f32_e32 v32, 0xbfb8aa3b, v59
	v_exp_f32_e32 v32, v32
	s_nop 0
	v_add_f32_e32 v32, 1.0, v32
	v_rcp_f32_e32 v34, v32
	s_nop 0
	v_mul_f32_e32 v32, v59, v34
	v_mul_f32_e32 v32, v43, v32
	v_cvt_pk_bf16_f32 v32, v32, s0
	ds_write_b16 v96, v32 offset:2736
	v_mul_f32_e32 v32, 0xbfb8aa3b, v60
	v_exp_f32_e32 v32, v32
	s_nop 0
	v_add_f32_e32 v32, 1.0, v32
	v_rcp_f32_e32 v34, v32
	s_nop 0
	v_mul_f32_e32 v32, v60, v34
	v_mul_f32_e32 v32, v44, v32
	v_cvt_pk_bf16_f32 v32, v32, s0
	ds_write_b16 v96, v32 offset:3456
	v_mul_f32_e32 v32, 0xbfb8aa3b, v61
	v_exp_f32_e32 v32, v32
	s_nop 0
	v_add_f32_e32 v32, 1.0, v32
	v_rcp_f32_e32 v34, v32
	s_nop 0
	v_mul_f32_e32 v32, v61, v34
	v_mul_f32_e32 v32, v45, v32
	v_cvt_pk_bf16_f32 v32, v32, s0
	ds_write_b16 v96, v32 offset:3600
	v_mul_f32_e32 v32, 0xbfb8aa3b, v62
	v_exp_f32_e32 v32, v32
	s_nop 0
	v_add_f32_e32 v32, 1.0, v32
	v_rcp_f32_e32 v34, v32
	s_nop 0
	v_mul_f32_e32 v32, v62, v34
	v_mul_f32_e32 v32, v46, v32
	v_cvt_pk_bf16_f32 v32, v32, s0
	ds_write_b16 v96, v32 offset:3744
	v_mul_f32_e32 v32, 0xbfb8aa3b, v63
	v_exp_f32_e32 v32, v32
	s_nop 0
	v_add_f32_e32 v32, 1.0, v32
	v_rcp_f32_e32 v34, v32
	s_nop 0
	v_mul_f32_e32 v32, v63, v34
	v_mul_f32_e32 v32, v47, v32
	v_cvt_pk_bf16_f32 v32, v32, s0
	ds_write_b16 v96, v32 offset:3888
	v_mul_f32_e32 v32, 0xbfb8aa3b, v16
	v_exp_f32_e32 v32, v32
	s_nop 0
	v_add_f32_e32 v32, 1.0, v32
	v_rcp_f32_e32 v34, v32
	s_nop 0
	v_mul_f32_e32 v16, v16, v34
	v_mul_f32_e32 v0, v0, v16
	v_cvt_pk_bf16_f32 v0, v0, s0
	ds_write_b16 v96, v0 offset:4608
	v_mul_f32_e32 v0, 0xbfb8aa3b, v17
	v_exp_f32_e32 v0, v0
	s_nop 0
	v_add_f32_e32 v0, 1.0, v0
	v_rcp_f32_e32 v32, v0
	s_nop 0
	v_mul_f32_e32 v0, v17, v32
	v_mul_f32_e32 v0, v1, v0
	v_cvt_pk_bf16_f32 v0, v0, s0
	ds_write_b16 v96, v0 offset:4752
	v_mul_f32_e32 v0, 0xbfb8aa3b, v18
	v_exp_f32_e32 v0, v0
	s_nop 0
	v_add_f32_e32 v0, 1.0, v0
	v_rcp_f32_e32 v16, v0
	s_nop 0
	v_mul_f32_e32 v0, v18, v16
	v_mul_f32_e32 v0, v2, v0
	v_cvt_pk_bf16_f32 v0, v0, s0
	ds_write_b16 v96, v0 offset:4896
	v_mul_f32_e32 v0, 0xbfb8aa3b, v19
	v_exp_f32_e32 v0, v0
	s_nop 0
	v_add_f32_e32 v0, 1.0, v0
	v_rcp_f32_e32 v2, v0
	s_nop 0
	v_mul_f32_e32 v0, v19, v2
	v_mul_f32_e32 v0, v3, v0
	v_cvt_pk_bf16_f32 v0, v0, s0
	ds_write_b16 v96, v0 offset:5040
	v_mul_f32_e32 v0, 0xbfb8aa3b, v20
	v_exp_f32_e32 v0, v0
	s_nop 0
	v_add_f32_e32 v0, 1.0, v0
	v_rcp_f32_e32 v2, v0
	s_nop 0
	v_mul_f32_e32 v0, v20, v2
	v_mul_f32_e32 v0, v4, v0
	v_cvt_pk_bf16_f32 v0, v0, s0
	ds_write_b16 v96, v0 offset:5760
	v_mul_f32_e32 v0, 0xbfb8aa3b, v21
	v_exp_f32_e32 v0, v0
	s_nop 0
	v_add_f32_e32 v0, 1.0, v0
	v_rcp_f32_e32 v2, v0
	s_nop 0
	v_mul_f32_e32 v0, v21, v2
	v_mul_f32_e32 v0, v5, v0
	v_cvt_pk_bf16_f32 v0, v0, s0
	ds_write_b16 v96, v0 offset:5904
	v_mul_f32_e32 v0, 0xbfb8aa3b, v22
	v_exp_f32_e32 v0, v0
	s_nop 0
	v_add_f32_e32 v0, 1.0, v0
	v_rcp_f32_e32 v2, v0
	s_nop 0
	v_mul_f32_e32 v0, v22, v2
	v_mul_f32_e32 v0, v6, v0
	v_cvt_pk_bf16_f32 v0, v0, s0
	ds_write_b16 v96, v0 offset:6048
	v_mul_f32_e32 v0, 0xbfb8aa3b, v23
	v_exp_f32_e32 v0, v0
	s_nop 0
	v_add_f32_e32 v0, 1.0, v0
	v_rcp_f32_e32 v2, v0
	s_nop 0
	v_mul_f32_e32 v0, v23, v2
	v_mul_f32_e32 v0, v7, v0
	v_cvt_pk_bf16_f32 v0, v0, s0
	ds_write_b16 v96, v0 offset:6192
	v_mul_f32_e32 v0, 0xbfb8aa3b, v24
	v_exp_f32_e32 v0, v0
	s_nop 0
	v_add_f32_e32 v0, 1.0, v0
	v_rcp_f32_e32 v2, v0
	s_nop 0
	v_mul_f32_e32 v0, v24, v2
	v_mul_f32_e32 v0, v8, v0
	v_cvt_pk_bf16_f32 v0, v0, s0
	ds_write_b16 v96, v0 offset:6912
	v_mul_f32_e32 v0, 0xbfb8aa3b, v25
	v_exp_f32_e32 v0, v0
	s_nop 0
	v_add_f32_e32 v0, 1.0, v0
	v_rcp_f32_e32 v2, v0
	s_nop 0
	v_mul_f32_e32 v0, v25, v2
	v_mul_f32_e32 v0, v9, v0
	v_cvt_pk_bf16_f32 v0, v0, s0
	ds_write_b16 v96, v0 offset:7056
	v_mul_f32_e32 v0, 0xbfb8aa3b, v26
	v_exp_f32_e32 v0, v0
	s_nop 0
	v_add_f32_e32 v0, 1.0, v0
	v_rcp_f32_e32 v2, v0
	s_nop 0
	v_mul_f32_e32 v0, v26, v2
	v_mul_f32_e32 v0, v10, v0
	v_cvt_pk_bf16_f32 v0, v0, s0
	ds_write_b16 v96, v0 offset:7200
	v_mul_f32_e32 v0, 0xbfb8aa3b, v27
	v_exp_f32_e32 v0, v0
	s_nop 0
	v_add_f32_e32 v0, 1.0, v0
	v_rcp_f32_e32 v2, v0
	s_nop 0
	v_mul_f32_e32 v0, v27, v2
	v_mul_f32_e32 v0, v11, v0
	v_cvt_pk_bf16_f32 v0, v0, s0
	ds_write_b16 v96, v0 offset:7344
	v_mul_f32_e32 v0, 0xbfb8aa3b, v28
	v_exp_f32_e32 v0, v0
	s_nop 0
	v_add_f32_e32 v0, 1.0, v0
	v_rcp_f32_e32 v2, v0
	s_nop 0
	v_mul_f32_e32 v0, v28, v2
	v_mul_f32_e32 v0, v12, v0
	v_cvt_pk_bf16_f32 v0, v0, s0
	ds_write_b16 v96, v0 offset:8064
	v_mul_f32_e32 v0, 0xbfb8aa3b, v29
	v_exp_f32_e32 v0, v0
	s_nop 0
	v_add_f32_e32 v0, 1.0, v0
	v_rcp_f32_e32 v2, v0
	s_nop 0
	v_mul_f32_e32 v0, v29, v2
	v_mul_f32_e32 v0, v13, v0
	v_cvt_pk_bf16_f32 v0, v0, s0
	ds_write_b16 v96, v0 offset:8208
	v_mul_f32_e32 v0, 0xbfb8aa3b, v30
	v_exp_f32_e32 v0, v0
	s_nop 0
	v_add_f32_e32 v0, 1.0, v0
	v_rcp_f32_e32 v2, v0
	s_nop 0
	v_mul_f32_e32 v0, v30, v2
	v_mul_f32_e32 v0, v14, v0
	v_cvt_pk_bf16_f32 v0, v0, s0
	ds_write_b16 v96, v0 offset:8352
	v_mul_f32_e32 v0, 0xbfb8aa3b, v31
	v_exp_f32_e32 v0, v0
	s_nop 0
	v_add_f32_e32 v0, 1.0, v0
	v_rcp_f32_e32 v2, v0
	s_nop 0
	v_mul_f32_e32 v0, v31, v2
	v_mul_f32_e32 v0, v15, v0
	v_cvt_pk_bf16_f32 v0, v0, s0
	ds_write_b16 v96, v0 offset:8496
	v_or_b32_e32 v4, 2, v68
	s_waitcnt lgkmcnt(0)
	v_ashrrev_i32_e32 v5, 31, v4
	ds_read_b128 v[0:3], v128
	v_mad_i64_i32 v[6:7], s[0:1], v71, s23, v[4:5]
	v_lshlrev_b64 v[6:7], 10, v[6:7]
	v_lshl_add_u64 v[6:7], s[66:67], 0, v[6:7]
	v_lshl_add_u64 v[6:7], v[6:7], 0, v[176:177]
	v_lshl_add_u64 v[8:9], v[6:7], 0, v[66:67]
	s_waitcnt lgkmcnt(0)
	global_store_dwordx4 v[8:9], v[0:3], off
	ds_read_b128 v[0:3], v128 offset:2304
	v_lshl_add_u64 v[6:7], v[6:7], 0, v[64:65]
	v_mad_i64_i32 v[4:5], s[0:1], v70, s23, v[4:5]
	v_lshlrev_b64 v[4:5], 10, v[4:5]
	s_waitcnt lgkmcnt(0)
	global_store_dwordx4 v[6:7], v[0:3], off
	ds_read_b128 v[0:3], v128 offset:4608
	v_lshl_add_u64 v[4:5], s[66:67], 0, v[4:5]
	v_lshl_add_u64 v[4:5], v[4:5], 0, v[176:177]
	v_lshl_add_u64 v[6:7], v[4:5], 0, v[66:67]
	v_lshl_add_u64 v[4:5], v[4:5], 0, v[64:65]
	s_waitcnt lgkmcnt(0)
	global_store_dwordx4 v[6:7], v[0:3], off
	ds_read_b128 v[0:3], v128 offset:6912
	v_readlane_b32 s0, v254, 11
	s_add_i32 s2, s2, s0
	s_cmp_lt_i32 s2, s3
	s_waitcnt lgkmcnt(0)
	global_store_dwordx4 v[4:5], v[0:3], off
	s_waitcnt lgkmcnt(0)
	s_barrier
	s_cbranch_scc1 .LBB0_1031

.LBB0_1086:
	s_ashr_i32 s6, s2, 31
	s_lshr_b32 s6, s6, 26
	s_add_i32 s6, s2, s6
	s_ashr_i32 s7, s6, 6
	s_lshl_b32 s7, s7, 3
	s_sub_i32 s8, s25, s7
	s_min_i32 s8, s8, 8
	s_abs_i32 s9, s8
	v_cvt_f32_u32_e32 v0, s9
	s_sub_i32 s12, 0, s9
	s_andn2_b32 s6, s6, 63
	s_sub_i32 s10, s2, s6
	v_rcp_iflag_f32_e32 v0, v0
	s_abs_i32 s6, s10
	s_xor_b32 s11, s10, s8
	s_ashr_i32 s11, s11, 31
	v_mul_f32_e32 v0, 0x4f7ffffe, v0
	v_cvt_u32_f32_e32 v0, v0
	v_mov_b32_e32 v181, v179
	v_readfirstlane_b32 s13, v0
	s_mul_i32 s12, s12, s13
	s_mul_hi_u32 s12, s13, s12
	s_add_i32 s13, s13, s12
	s_mul_hi_u32 s12, s6, s13
	s_mul_i32 s13, s12, s9
	s_sub_i32 s6, s6, s13
	s_add_i32 s14, s12, 1
	s_sub_i32 s13, s6, s9
	s_cmp_ge_u32 s6, s9
	s_cselect_b32 s12, s14, s12
	s_cselect_b32 s6, s13, s6
	s_add_i32 s13, s12, 1
	s_cmp_ge_u32 s6, s9
	s_cselect_b32 s6, s13, s12
	s_xor_b32 s6, s6, s11
	s_sub_i32 s6, s6, s11
	s_mul_i32 s8, s8, s6
	s_add_i32 s7, s7, s5
	s_sub_i32 s8, s10, s8
	v_ashrrev_i32_e32 v237, 6, v181
	s_add_i32 s7, s7, s8
	v_lshlrev_b32_e32 v0, 1, v237
	v_bfe_u32 v183, v181, 5, 1
	v_lshl_add_u32 v2, s7, 3, v0
	v_mov_b64_e32 v[0:1], s[66:67]
	v_and_b32_e32 v238, 31, v181
	v_mad_i64_i32 v[0:1], s[8:9], v2, s24, v[0:1]
	v_lshlrev_b32_e32 v176, 9, v183
	v_lshl_add_u64 v[0:1], v[0:1], 0, v[176:177]
	v_lshlrev_b32_e32 v176, 4, v238
	v_ashrrev_i32_e32 v38, 2, v181
	s_mul_i32 s8, s6, 0xb0000
	v_lshl_add_u64 v[184:185], v[0:1], 0, v[176:177]
	s_mul_hi_i32 s9, s6, 0xb0000
	s_add_u32 s8, s3, s8
	v_lshlrev_b32_e32 v0, 5, v38
	s_addc_u32 s9, s4, s9
	v_ashrrev_i32_e32 v1, 31, v0
	v_lshlrev_b32_e32 v2, 4, v181
	v_lshl_add_u64 v[0:1], v[0:1], 1, s[8:9]
	v_and_b32_e32 v176, 48, v2
	v_lshl_add_u64 v[186:187], v[0:1], 0, v[176:177]
	s_movk_i32 s8, 0x2000
	v_add_co_u32_e32 v34, vcc, s8, v186
	v_mul_u32_u24_e32 v36, 40, v238
	s_nop 0
	v_addc_co_u32_e32 v35, vcc, 0, v187, vcc
	v_lshlrev_b32_e32 v37, 4, v183
	v_lshl_add_u32 v240, v36, 1, v37
	v_add_co_u32_e32 v36, vcc, s24, v184
	s_movk_i32 s9, 0x50
	s_nop 0
	v_addc_co_u32_e32 v37, vcc, 0, v185, vcc
	v_and_b32_e32 v239, 63, v181
	v_lshrrev_b32_e32 v176, 6, v181
	v_lshlrev_b32_e32 v247, 11, v176
	s_nop 0
	v_readfirstlane_b32 vcc_lo, v247
	v_bfe_u32 v247, v181, 4, 2
	v_lshlrev_b32_e32 v247, 1, v247
	v_mov_b32_e32 v176, 0x78
	v_lshrrev_b32_e32 v247, v247, v176
	v_and_b32_e32 v247, 3, v247
	v_and_b32_e32 v246, 3, v181
	v_xor_b32_e32 v247, v247, v246
	v_lshlrev_b32_e32 v247, 4, v247
	v_and_b32_e32 v188, 0xffffffcf, v186
	v_or_b32_e32 v188, v188, v247
	v_mov_b32_e32 v189, v187
	v_lshrrev_b32_e32 v176, 6, v181
	v_lshlrev_b32_e32 v176, 10, v176
	v_lshl_add_u64 v[188:189], v[188:189], 0, v[176:177]
	v_bfe_u32 v247, v181, 4, 1
	v_lshlrev_b32_e32 v176, 9, v183
	v_lshl_add_u32 v176, v247, 8, v176
	v_lshl_add_u64 v[184:185], v[184:185], 0, v[176:177]
	v_mov_b32_e32 v176, s24
	v_lshl_add_u64 v[186:187], v[184:185], 0, v[176:177]
	v_mov_b32_e32 v176, 0x78
	v_bfe_u32 v247, v181, 2, 2
	v_lshlrev_b32_e32 v247, 1, v247
	v_lshrrev_b32_e32 v247, v247, v176
	v_and_b32_e32 v247, 3, v247
	v_bfe_u32 v246, v181, 4, 2
	v_xor_b32_e32 v247, v247, v246
	v_lshlrev_b32_e32 v247, 4, v247
	v_and_b32_e32 v246, 15, v181
	v_lshl_add_u32 v246, v246, 6, v247
	s_mov_b32 s96, 0
	s_mov_b32 m0, vcc_lo
	v_lshl_add_u64 v[160:161], v[188:189], 0, s[96:97]
	global_load_lds_dwordx4 v[160:161], off
	global_load_lds_dwordx4 v[160:161], off offset:1024
	s_mov_b32 s96, 0
	v_lshl_add_u64 v[248:249], v[184:185], 0, s[96:97]
	v_lshl_add_u64 v[250:251], v[186:187], 0, s[96:97]
	global_load_dwordx4 v[128:131], v[248:249], off
	global_load_dwordx4 v[132:135], v[248:249], off offset:256
	global_load_dwordx4 v[136:139], v[250:251], off
	global_load_dwordx4 v[140:143], v[250:251], off offset:256
	s_movk_i32 s96, 0x2000
	s_add_i32 m0, vcc_lo, 8192
	v_lshl_add_u64 v[160:161], v[188:189], 0, s[96:97]
	global_load_lds_dwordx4 v[160:161], off
	global_load_lds_dwordx4 v[160:161], off offset:1024
	s_movk_i32 s96, 0x800
	v_lshl_add_u64 v[248:249], v[184:185], 0, s[96:97]
	v_lshl_add_u64 v[250:251], v[186:187], 0, s[96:97]
	global_load_dwordx4 v[144:147], v[248:249], off
	global_load_dwordx4 v[148:151], v[248:249], off offset:256
	global_load_dwordx4 v[152:155], v[250:251], off
	global_load_dwordx4 v[156:159], v[250:251], off offset:256
	v_mov_b32_e32 v0, 0
	v_mov_b32_e32 v1, 0
	v_mov_b32_e32 v2, 0
	v_mov_b32_e32 v3, 0
	v_mov_b32_e32 v4, 0
	v_mov_b32_e32 v5, 0
	v_mov_b32_e32 v6, 0
	v_mov_b32_e32 v7, 0
	v_mov_b32_e32 v8, 0
	v_mov_b32_e32 v9, 0
	v_mov_b32_e32 v10, 0
	v_mov_b32_e32 v11, 0
	v_mov_b32_e32 v12, 0
	v_mov_b32_e32 v13, 0
	v_mov_b32_e32 v14, 0
	v_mov_b32_e32 v15, 0
	v_mov_b32_e32 v16, 0
	v_mov_b32_e32 v17, 0
	v_mov_b32_e32 v18, 0
	v_mov_b32_e32 v19, 0
	v_mov_b32_e32 v20, 0
	v_mov_b32_e32 v21, 0
	v_mov_b32_e32 v22, 0
	v_mov_b32_e32 v23, 0
	v_mov_b32_e32 v24, 0
	v_mov_b32_e32 v25, 0
	v_mov_b32_e32 v26, 0
	v_mov_b32_e32 v27, 0
	v_mov_b32_e32 v28, 0
	v_mov_b32_e32 v29, 0
	v_mov_b32_e32 v30, 0
	v_mov_b32_e32 v31, 0
	v_mov_b32_e32 v32, 0
	v_mov_b32_e32 v33, 0
	v_mov_b32_e32 v34, 0
	v_mov_b32_e32 v35, 0
	v_mov_b32_e32 v36, 0
	v_mov_b32_e32 v37, 0
	v_mov_b32_e32 v38, 0
	v_mov_b32_e32 v39, 0
	v_mov_b32_e32 v40, 0
	v_mov_b32_e32 v41, 0
	v_mov_b32_e32 v42, 0
	v_mov_b32_e32 v43, 0
	v_mov_b32_e32 v44, 0
	v_mov_b32_e32 v45, 0
	v_mov_b32_e32 v46, 0
	v_mov_b32_e32 v47, 0
	v_mov_b32_e32 v48, 0
	v_mov_b32_e32 v49, 0
	v_mov_b32_e32 v50, 0
	v_mov_b32_e32 v51, 0
	v_mov_b32_e32 v52, 0
	v_mov_b32_e32 v53, 0
	v_mov_b32_e32 v54, 0
	v_mov_b32_e32 v55, 0
	v_mov_b32_e32 v56, 0
	v_mov_b32_e32 v57, 0
	v_mov_b32_e32 v58, 0
	v_mov_b32_e32 v59, 0
	v_mov_b32_e32 v60, 0
	v_mov_b32_e32 v61, 0
	v_mov_b32_e32 v62, 0
	v_mov_b32_e32 v63, 0
	v_mov_b32_e32 v64, 0
	v_mov_b32_e32 v65, 0
	v_mov_b32_e32 v66, 0
	v_mov_b32_e32 v67, 0
	v_mov_b32_e32 v68, 0
	v_mov_b32_e32 v69, 0
	v_mov_b32_e32 v70, 0
	v_mov_b32_e32 v71, 0
	v_mov_b32_e32 v72, 0
	v_mov_b32_e32 v73, 0
	v_mov_b32_e32 v74, 0
	v_mov_b32_e32 v75, 0
	v_mov_b32_e32 v76, 0
	v_mov_b32_e32 v77, 0
	v_mov_b32_e32 v78, 0
	v_mov_b32_e32 v79, 0
	v_mov_b32_e32 v80, 0
	v_mov_b32_e32 v81, 0
	v_mov_b32_e32 v82, 0
	v_mov_b32_e32 v83, 0
	v_mov_b32_e32 v84, 0
	v_mov_b32_e32 v85, 0
	v_mov_b32_e32 v86, 0
	v_mov_b32_e32 v87, 0
	v_mov_b32_e32 v88, 0
	v_mov_b32_e32 v89, 0
	v_mov_b32_e32 v90, 0
	v_mov_b32_e32 v91, 0
	v_mov_b32_e32 v92, 0
	v_mov_b32_e32 v93, 0
	v_mov_b32_e32 v94, 0
	v_mov_b32_e32 v95, 0
	v_mov_b32_e32 v96, 0
	v_mov_b32_e32 v97, 0
	v_mov_b32_e32 v98, 0
	v_mov_b32_e32 v99, 0
	v_mov_b32_e32 v100, 0
	v_mov_b32_e32 v101, 0
	v_mov_b32_e32 v102, 0
	v_mov_b32_e32 v103, 0
	v_mov_b32_e32 v104, 0
	v_mov_b32_e32 v105, 0
	v_mov_b32_e32 v106, 0
	v_mov_b32_e32 v107, 0
	v_mov_b32_e32 v108, 0
	v_mov_b32_e32 v109, 0
	v_mov_b32_e32 v110, 0
	v_mov_b32_e32 v111, 0
	v_mov_b32_e32 v112, 0
	v_mov_b32_e32 v113, 0
	v_mov_b32_e32 v114, 0
	v_mov_b32_e32 v115, 0
	v_mov_b32_e32 v116, 0
	v_mov_b32_e32 v117, 0
	v_mov_b32_e32 v118, 0
	v_mov_b32_e32 v119, 0
	v_mov_b32_e32 v120, 0
	v_mov_b32_e32 v121, 0
	v_mov_b32_e32 v122, 0
	v_mov_b32_e32 v123, 0
	v_mov_b32_e32 v124, 0
	v_mov_b32_e32 v125, 0
	v_mov_b32_e32 v126, 0
	v_mov_b32_e32 v127, 0
	s_mov_b32 s8, 0
	s_waitcnt vmcnt(4)
	s_barrier
